# leading half-workgroup defers its LDS-read wait to after the barrier in every GEMM K-loop load segment (only the trailing half's reads race the restage)
# speedup vs baseline: 1.0032x; 1.0032x over previous
.LBB0_215:
	s_ashr_i32 s13, s12, 31
	s_lshl_b64 s[16:17], s[12:13], 21
	s_add_u32 s16, s70, s16
	s_addc_u32 s17, s71, s17
	s_and_b64 s[18:19], s[2:3], exec
	s_cselect_b32 s13, s17, s1
	s_cselect_b32 s24, s16, s0
	s_ashr_i32 s15, s14, 31
	s_lshl_b64 s[18:19], s[14:15], 21
	s_add_u32 s18, s6, s18
	s_addc_u32 s19, s7, s19
	s_and_b64 s[22:23], s[2:3], exec
	s_cselect_b32 s15, s19, s21
	s_cselect_b32 s25, s18, s20
	s_add_u32 s0, s0, 0x100080
	s_addc_u32 s1, s1, 0
	s_add_u32 s27, s20, 0x100
	v_mov_b32_e32 v2, 0
	s_addc_u32 s29, s21, 0
	s_mov_b32 s30, -2
	v_mov_b64_e32 v[2:3], 0
	v_mov_b64_e32 v[4:5], 0
	v_mov_b64_e32 v[6:7], 0
	v_mov_b64_e32 v[8:9], 0
	v_mov_b64_e32 v[10:11], 0
	v_mov_b64_e32 v[12:13], 0
	v_mov_b64_e32 v[14:15], 0
	v_mov_b64_e32 v[16:17], 0
	v_mov_b64_e32 v[18:19], 0
	v_mov_b64_e32 v[20:21], 0
	v_mov_b64_e32 v[22:23], 0
	v_mov_b64_e32 v[24:25], 0
	v_mov_b64_e32 v[26:27], 0
	v_mov_b64_e32 v[28:29], 0
	v_mov_b64_e32 v[30:31], 0
	v_mov_b64_e32 v[32:33], 0
	v_mov_b64_e32 v[34:35], 0
	v_mov_b64_e32 v[36:37], 0
	v_mov_b64_e32 v[38:39], 0
	v_mov_b64_e32 v[40:41], 0
	v_mov_b64_e32 v[42:43], 0
	v_mov_b64_e32 v[44:45], 0
	v_mov_b64_e32 v[46:47], 0
	v_mov_b64_e32 v[48:49], 0
	v_mov_b64_e32 v[50:51], 0
	v_mov_b64_e32 v[52:53], 0
	v_mov_b64_e32 v[54:55], 0
	v_mov_b64_e32 v[56:57], 0
	v_mov_b64_e32 v[58:59], 0
	v_mov_b64_e32 v[60:61], 0
	v_mov_b64_e32 v[62:63], 0
	v_mov_b64_e32 v[64:65], 0
	v_mov_b64_e32 v[66:67], 0
	v_mov_b64_e32 v[68:69], 0
	v_mov_b64_e32 v[70:71], 0
	v_mov_b64_e32 v[72:73], 0
	v_mov_b64_e32 v[74:75], 0
	v_mov_b64_e32 v[76:77], 0
	v_mov_b64_e32 v[78:79], 0
	v_mov_b64_e32 v[80:81], 0
	v_mov_b64_e32 v[82:83], 0
	v_mov_b64_e32 v[84:85], 0
	v_mov_b64_e32 v[86:87], 0
	v_mov_b64_e32 v[88:89], 0
	v_mov_b64_e32 v[90:91], 0
	v_mov_b64_e32 v[92:93], 0
	v_mov_b64_e32 v[94:95], 0
	v_mov_b64_e32 v[96:97], 0
	v_mov_b64_e32 v[98:99], 0
	v_mov_b64_e32 v[100:101], 0
	v_mov_b64_e32 v[102:103], 0
	v_mov_b64_e32 v[104:105], 0
	v_mov_b64_e32 v[106:107], 0
	v_mov_b64_e32 v[108:109], 0
	v_mov_b64_e32 v[110:111], 0
	v_mov_b64_e32 v[112:113], 0
	v_mov_b64_e32 v[114:115], 0
	v_mov_b64_e32 v[116:117], 0
	v_mov_b64_e32 v[118:119], 0
	v_mov_b64_e32 v[120:121], 0
	v_mov_b64_e32 v[122:123], 0
	v_mov_b64_e32 v[124:125], 0
	v_mov_b64_e32 v[126:127], 0
	v_mov_b64_e32 v[128:129], 0
	v_add_u32_e32 v246, 0x18000, v158
	v_add_u32_e32 v247, 0x1c000, v158
	v_cmp_gt_u32_e32 vcc, 0x100, v0
.LBB0_216:
	ds_read_b128 v[152:155], v160
	ds_read_b128 v[164:167], v160 offset:1024
	ds_read_b128 v[168:171], v160 offset:2048
	ds_read_b128 v[172:175], v160 offset:3072
	ds_read_b128 v[176:179], v161
	ds_read_b128 v[180:183], v161 offset:1024
	ds_read_b128 v[184:187], v161 offset:2048
	ds_read_b128 v[188:191], v161 offset:3072
	s_add_u32 s20, s0, 0xfff00080
	s_addc_u32 s21, s1, -1
	s_cmp_eq_u32 s30, 60
	s_cselect_b32 s23, s13, s21
	s_cselect_b32 s22, s24, s20
	s_cselect_b32 s21, s15, s29
	s_cselect_b32 s20, s25, s27
	s_add_i32 m0, s39, 0xc000
	ds_read_b128 v[192:195], v162
	ds_read_b128 v[196:199], v162 offset:1024
	ds_read_b128 v[200:203], v162 offset:2048
	ds_read_b128 v[204:207], v162 offset:3072
	ds_read_b128 v[208:211], v162 offset:4096
	ds_read_b128 v[212:215], v162 offset:5120
	ds_read_b128 v[216:219], v162 offset:6144
	ds_read_b128 v[220:223], v162 offset:7168
	global_load_lds_dwordx4 v140, s[0:1]
	s_add_i32 m0, s39, 0xe000
	s_nop 0
	global_load_lds_dwordx4 v142, s[0:1]
	s_waitcnt vmcnt(8)
	s_cbranch_vccnz .Ldefl_216_0
	s_waitcnt lgkmcnt(0)
.Ldefl_216_0:
	s_barrier
	s_waitcnt lgkmcnt(0)
	v_mfma_f32_16x16x32_bf16 v[126:129], v[152:155], v[192:195], v[126:129]
	v_mfma_f32_16x16x32_bf16 v[126:129], v[164:167], v[196:199], v[126:129]
	v_mfma_f32_16x16x32_bf16 v[122:125], v[168:171], v[192:195], v[122:125]
	v_mfma_f32_16x16x32_bf16 v[122:125], v[172:175], v[196:199], v[122:125]
	v_mfma_f32_16x16x32_bf16 v[114:117], v[152:155], v[200:203], v[114:117]
	v_mfma_f32_16x16x32_bf16 v[114:117], v[164:167], v[204:207], v[114:117]
	v_mfma_f32_16x16x32_bf16 v[106:109], v[168:171], v[200:203], v[106:109]
	v_mfma_f32_16x16x32_bf16 v[106:109], v[172:175], v[204:207], v[106:109]
	v_mfma_f32_16x16x32_bf16 v[98:101], v[152:155], v[208:211], v[98:101]
	v_mfma_f32_16x16x32_bf16 v[98:101], v[164:167], v[212:215], v[98:101]
	v_mfma_f32_16x16x32_bf16 v[90:93], v[168:171], v[208:211], v[90:93]
	v_mfma_f32_16x16x32_bf16 v[90:93], v[172:175], v[212:215], v[90:93]
	v_mfma_f32_16x16x32_bf16 v[82:85], v[152:155], v[216:219], v[82:85]
	v_mfma_f32_16x16x32_bf16 v[82:85], v[164:167], v[220:223], v[82:85]
	v_mfma_f32_16x16x32_bf16 v[74:77], v[168:171], v[216:219], v[74:77]
	v_mfma_f32_16x16x32_bf16 v[74:77], v[172:175], v[220:223], v[74:77]
	v_mfma_f32_16x16x32_bf16 v[118:121], v[176:179], v[192:195], v[118:121]
	v_mfma_f32_16x16x32_bf16 v[118:121], v[180:183], v[196:199], v[118:121]
	v_mfma_f32_16x16x32_bf16 v[110:113], v[184:187], v[192:195], v[110:113]
	v_mfma_f32_16x16x32_bf16 v[110:113], v[188:191], v[196:199], v[110:113]
	v_mfma_f32_16x16x32_bf16 v[102:105], v[176:179], v[200:203], v[102:105]
	v_mfma_f32_16x16x32_bf16 v[102:105], v[180:183], v[204:207], v[102:105]
	v_mfma_f32_16x16x32_bf16 v[94:97], v[184:187], v[200:203], v[94:97]
	v_mfma_f32_16x16x32_bf16 v[94:97], v[188:191], v[204:207], v[94:97]
	v_mfma_f32_16x16x32_bf16 v[86:89], v[176:179], v[208:211], v[86:89]
	v_mfma_f32_16x16x32_bf16 v[86:89], v[180:183], v[212:215], v[86:89]
	v_mfma_f32_16x16x32_bf16 v[78:81], v[184:187], v[208:211], v[78:81]
	v_mfma_f32_16x16x32_bf16 v[78:81], v[188:191], v[212:215], v[78:81]
	v_mfma_f32_16x16x32_bf16 v[70:73], v[176:179], v[216:219], v[70:73]
	v_mfma_f32_16x16x32_bf16 v[70:73], v[180:183], v[220:223], v[70:73]
	v_mfma_f32_16x16x32_bf16 v[66:69], v[184:187], v[216:219], v[66:69]
	v_mfma_f32_16x16x32_bf16 v[66:69], v[188:191], v[220:223], v[66:69]
	s_barrier
	s_add_i32 s31, s49, s38
	s_mov_b32 m0, s31
	ds_read_b128 v[192:195], v162 offset:16384
	ds_read_b128 v[196:199], v162 offset:17408
	ds_read_b128 v[200:203], v162 offset:18432
	ds_read_b128 v[204:207], v162 offset:19456
	ds_read_b128 v[208:211], v162 offset:20480
	ds_read_b128 v[212:215], v162 offset:21504
	ds_read_b128 v[216:219], v162 offset:22528
	ds_read_b128 v[220:223], v162 offset:23552
	global_load_lds_dwordx4 v132, s[20:21]
	s_add_i32 m0, s31, 0x2000
	s_add_u32 s34, s20, 0x100000
	s_addc_u32 s35, s21, 0
	s_add_i32 s31, s50, s38
	global_load_lds_dwordx4 v136, s[20:21]
	s_mov_b32 m0, s31
	global_load_lds_dwordx4 v132, s[34:35]
	s_add_i32 m0, s31, 0x2000
	s_nop 0
	global_load_lds_dwordx4 v136, s[34:35]
	s_mov_b32 m0, s39
	s_nop 0
	global_load_lds_dwordx4 v130, s[22:23]
	s_mov_b32 m0, s40
	s_nop 0
	global_load_lds_dwordx4 v134, s[22:23]
	s_waitcnt vmcnt(8)
	s_cbranch_vccnz .Ldefl_216_1
	s_waitcnt lgkmcnt(0)
.Ldefl_216_1:
	s_barrier
	s_waitcnt lgkmcnt(0)
	v_mfma_f32_16x16x32_bf16 v[62:65], v[152:155], v[192:195], v[62:65]
	v_mfma_f32_16x16x32_bf16 v[62:65], v[164:167], v[196:199], v[62:65]
	v_mfma_f32_16x16x32_bf16 v[58:61], v[168:171], v[192:195], v[58:61]
	v_mfma_f32_16x16x32_bf16 v[58:61], v[172:175], v[196:199], v[58:61]
	v_mfma_f32_16x16x32_bf16 v[46:49], v[152:155], v[200:203], v[46:49]
	v_mfma_f32_16x16x32_bf16 v[46:49], v[164:167], v[204:207], v[46:49]
	v_mfma_f32_16x16x32_bf16 v[42:45], v[168:171], v[200:203], v[42:45]
	v_mfma_f32_16x16x32_bf16 v[42:45], v[172:175], v[204:207], v[42:45]
	v_mfma_f32_16x16x32_bf16 v[30:33], v[152:155], v[208:211], v[30:33]
	v_mfma_f32_16x16x32_bf16 v[30:33], v[164:167], v[212:215], v[30:33]
	v_mfma_f32_16x16x32_bf16 v[26:29], v[168:171], v[208:211], v[26:29]
	v_mfma_f32_16x16x32_bf16 v[26:29], v[172:175], v[212:215], v[26:29]
	v_mfma_f32_16x16x32_bf16 v[14:17], v[152:155], v[216:219], v[14:17]
	v_mfma_f32_16x16x32_bf16 v[14:17], v[164:167], v[220:223], v[14:17]
	v_mfma_f32_16x16x32_bf16 v[10:13], v[168:171], v[216:219], v[10:13]
	v_mfma_f32_16x16x32_bf16 v[10:13], v[172:175], v[220:223], v[10:13]
	v_mfma_f32_16x16x32_bf16 v[54:57], v[176:179], v[192:195], v[54:57]
	v_mfma_f32_16x16x32_bf16 v[54:57], v[180:183], v[196:199], v[54:57]
	v_mfma_f32_16x16x32_bf16 v[50:53], v[184:187], v[192:195], v[50:53]
	v_mfma_f32_16x16x32_bf16 v[50:53], v[188:191], v[196:199], v[50:53]
	v_mfma_f32_16x16x32_bf16 v[38:41], v[176:179], v[200:203], v[38:41]
	v_mfma_f32_16x16x32_bf16 v[38:41], v[180:183], v[204:207], v[38:41]
	v_mfma_f32_16x16x32_bf16 v[34:37], v[184:187], v[200:203], v[34:37]
	v_mfma_f32_16x16x32_bf16 v[34:37], v[188:191], v[204:207], v[34:37]
	v_mfma_f32_16x16x32_bf16 v[22:25], v[176:179], v[208:211], v[22:25]
	v_mfma_f32_16x16x32_bf16 v[22:25], v[180:183], v[212:215], v[22:25]
	v_mfma_f32_16x16x32_bf16 v[18:21], v[184:187], v[208:211], v[18:21]
	v_mfma_f32_16x16x32_bf16 v[18:21], v[188:191], v[212:215], v[18:21]
	v_mfma_f32_16x16x32_bf16 v[6:9], v[176:179], v[216:219], v[6:9]
	v_mfma_f32_16x16x32_bf16 v[6:9], v[180:183], v[220:223], v[6:9]
	v_mfma_f32_16x16x32_bf16 v[2:5], v[184:187], v[216:219], v[2:5]
	v_mfma_f32_16x16x32_bf16 v[2:5], v[188:191], v[220:223], v[2:5]
	s_barrier
	s_add_i32 s31, 0, 0x18000
	s_add_i32 s33, 0, 0x1c000
	ds_read_b128 v[152:155], v246
	ds_read_b128 v[164:167], v246 offset:1024
	ds_read_b128 v[168:171], v246 offset:2048
	ds_read_b128 v[172:175], v246 offset:3072
	ds_read_b128 v[176:179], v247
	ds_read_b128 v[180:183], v247 offset:1024
	ds_read_b128 v[184:187], v247 offset:2048
	ds_read_b128 v[188:191], v247 offset:3072
	s_add_u32 s98, s22, 0x80
	s_addc_u32 s99, s23, 0
	s_add_u32 s22, s22, 0x100000
	s_addc_u32 s23, s23, 0
	s_mov_b32 m0, s41
	ds_read_b128 v[192:195], v162 offset:32768
	ds_read_b128 v[196:199], v162 offset:33792
	ds_read_b128 v[200:203], v162 offset:34816
	ds_read_b128 v[204:207], v162 offset:35840
	ds_read_b128 v[208:211], v162 offset:36864
	ds_read_b128 v[212:215], v162 offset:37888
	ds_read_b128 v[216:219], v162 offset:38912
	ds_read_b128 v[220:223], v162 offset:39936
	global_load_lds_dwordx4 v130, s[22:23]
	s_mov_b32 m0, s42
	s_nop 0
	global_load_lds_dwordx4 v134, s[22:23]
	s_waitcnt vmcnt(8)
	s_cbranch_vccnz .Ldefl_216_2
	s_waitcnt lgkmcnt(0)
.Ldefl_216_2:
	s_barrier
	s_waitcnt lgkmcnt(0)
	v_mfma_f32_16x16x32_bf16 v[126:129], v[152:155], v[192:195], v[126:129]
	v_mfma_f32_16x16x32_bf16 v[126:129], v[164:167], v[196:199], v[126:129]
	v_mfma_f32_16x16x32_bf16 v[122:125], v[168:171], v[192:195], v[122:125]
	v_mfma_f32_16x16x32_bf16 v[122:125], v[172:175], v[196:199], v[122:125]
	v_mfma_f32_16x16x32_bf16 v[114:117], v[152:155], v[200:203], v[114:117]
	v_mfma_f32_16x16x32_bf16 v[114:117], v[164:167], v[204:207], v[114:117]
	v_mfma_f32_16x16x32_bf16 v[106:109], v[168:171], v[200:203], v[106:109]
	v_mfma_f32_16x16x32_bf16 v[106:109], v[172:175], v[204:207], v[106:109]
	v_mfma_f32_16x16x32_bf16 v[98:101], v[152:155], v[208:211], v[98:101]
	v_mfma_f32_16x16x32_bf16 v[98:101], v[164:167], v[212:215], v[98:101]
	v_mfma_f32_16x16x32_bf16 v[90:93], v[168:171], v[208:211], v[90:93]
	v_mfma_f32_16x16x32_bf16 v[90:93], v[172:175], v[212:215], v[90:93]
	v_mfma_f32_16x16x32_bf16 v[82:85], v[152:155], v[216:219], v[82:85]
	v_mfma_f32_16x16x32_bf16 v[82:85], v[164:167], v[220:223], v[82:85]
	v_mfma_f32_16x16x32_bf16 v[74:77], v[168:171], v[216:219], v[74:77]
	v_mfma_f32_16x16x32_bf16 v[74:77], v[172:175], v[220:223], v[74:77]
	v_mfma_f32_16x16x32_bf16 v[118:121], v[176:179], v[192:195], v[118:121]
	v_mfma_f32_16x16x32_bf16 v[118:121], v[180:183], v[196:199], v[118:121]
	v_mfma_f32_16x16x32_bf16 v[110:113], v[184:187], v[192:195], v[110:113]
	v_mfma_f32_16x16x32_bf16 v[110:113], v[188:191], v[196:199], v[110:113]
	v_mfma_f32_16x16x32_bf16 v[102:105], v[176:179], v[200:203], v[102:105]
	v_mfma_f32_16x16x32_bf16 v[102:105], v[180:183], v[204:207], v[102:105]
	v_mfma_f32_16x16x32_bf16 v[94:97], v[184:187], v[200:203], v[94:97]
	v_mfma_f32_16x16x32_bf16 v[94:97], v[188:191], v[204:207], v[94:97]
	v_mfma_f32_16x16x32_bf16 v[86:89], v[176:179], v[208:211], v[86:89]
	v_mfma_f32_16x16x32_bf16 v[86:89], v[180:183], v[212:215], v[86:89]
	v_mfma_f32_16x16x32_bf16 v[78:81], v[184:187], v[208:211], v[78:81]
	v_mfma_f32_16x16x32_bf16 v[78:81], v[188:191], v[212:215], v[78:81]
	v_mfma_f32_16x16x32_bf16 v[70:73], v[176:179], v[216:219], v[70:73]
	v_mfma_f32_16x16x32_bf16 v[70:73], v[180:183], v[220:223], v[70:73]
	v_mfma_f32_16x16x32_bf16 v[66:69], v[184:187], v[216:219], v[66:69]
	v_mfma_f32_16x16x32_bf16 v[66:69], v[188:191], v[220:223], v[66:69]
	s_barrier
	s_add_i32 s22, s31, s38
	s_mov_b32 m0, s22
	ds_read_b128 v[192:195], v162 offset:49152
	ds_read_b128 v[196:199], v162 offset:50176
	ds_read_b128 v[200:203], v162 offset:51200
	ds_read_b128 v[204:207], v162 offset:52224
	ds_read_b128 v[208:211], v162 offset:53248
	ds_read_b128 v[212:215], v162 offset:54272
	ds_read_b128 v[216:219], v162 offset:55296
	ds_read_b128 v[220:223], v162 offset:56320
	s_add_u32 s20, s20, 0x80
	s_addc_u32 s21, s21, 0
	global_load_lds_dwordx4 v132, s[20:21]
	s_add_i32 m0, s22, 0x2000
	s_add_i32 s22, s33, s38
	global_load_lds_dwordx4 v136, s[20:21]
	s_add_u32 s20, s20, 0x100000
	s_addc_u32 s21, s21, 0
	s_mov_b32 m0, s22
	s_nop 0
	global_load_lds_dwordx4 v132, s[20:21]
	s_add_i32 m0, s22, 0x2000
	s_nop 0
	global_load_lds_dwordx4 v136, s[20:21]
	s_mov_b32 m0, s45
	s_nop 0
	global_load_lds_dwordx4 v130, s[98:99]
	s_mov_b32 m0, s46
	s_nop 0
	global_load_lds_dwordx4 v134, s[98:99]
	s_waitcnt vmcnt(8)
	s_cbranch_vccnz .Ldefl_216_3
	s_waitcnt lgkmcnt(0)
.Ldefl_216_3:
	s_barrier
	s_waitcnt lgkmcnt(0)
	v_mfma_f32_16x16x32_bf16 v[62:65], v[152:155], v[192:195], v[62:65]
	v_mfma_f32_16x16x32_bf16 v[62:65], v[164:167], v[196:199], v[62:65]
	v_mfma_f32_16x16x32_bf16 v[58:61], v[168:171], v[192:195], v[58:61]
	v_mfma_f32_16x16x32_bf16 v[58:61], v[172:175], v[196:199], v[58:61]
	v_mfma_f32_16x16x32_bf16 v[46:49], v[152:155], v[200:203], v[46:49]
	v_mfma_f32_16x16x32_bf16 v[46:49], v[164:167], v[204:207], v[46:49]
	v_mfma_f32_16x16x32_bf16 v[42:45], v[168:171], v[200:203], v[42:45]
	v_mfma_f32_16x16x32_bf16 v[42:45], v[172:175], v[204:207], v[42:45]
	v_mfma_f32_16x16x32_bf16 v[30:33], v[152:155], v[208:211], v[30:33]
	v_mfma_f32_16x16x32_bf16 v[30:33], v[164:167], v[212:215], v[30:33]
	v_mfma_f32_16x16x32_bf16 v[26:29], v[168:171], v[208:211], v[26:29]
	v_mfma_f32_16x16x32_bf16 v[26:29], v[172:175], v[212:215], v[26:29]
	v_mfma_f32_16x16x32_bf16 v[14:17], v[152:155], v[216:219], v[14:17]
	v_mfma_f32_16x16x32_bf16 v[14:17], v[164:167], v[220:223], v[14:17]
	v_mfma_f32_16x16x32_bf16 v[10:13], v[168:171], v[216:219], v[10:13]
	v_mfma_f32_16x16x32_bf16 v[10:13], v[172:175], v[220:223], v[10:13]
	v_mfma_f32_16x16x32_bf16 v[54:57], v[176:179], v[192:195], v[54:57]
	v_mfma_f32_16x16x32_bf16 v[54:57], v[180:183], v[196:199], v[54:57]
	v_mfma_f32_16x16x32_bf16 v[50:53], v[184:187], v[192:195], v[50:53]
	v_mfma_f32_16x16x32_bf16 v[50:53], v[188:191], v[196:199], v[50:53]
	v_mfma_f32_16x16x32_bf16 v[38:41], v[176:179], v[200:203], v[38:41]
	v_mfma_f32_16x16x32_bf16 v[38:41], v[180:183], v[204:207], v[38:41]
	v_mfma_f32_16x16x32_bf16 v[34:37], v[184:187], v[200:203], v[34:37]
	v_mfma_f32_16x16x32_bf16 v[34:37], v[188:191], v[204:207], v[34:37]
	v_mfma_f32_16x16x32_bf16 v[22:25], v[176:179], v[208:211], v[22:25]
	v_mfma_f32_16x16x32_bf16 v[22:25], v[180:183], v[212:215], v[22:25]
	v_mfma_f32_16x16x32_bf16 v[18:21], v[184:187], v[208:211], v[18:21]
	v_mfma_f32_16x16x32_bf16 v[18:21], v[188:191], v[212:215], v[18:21]
	v_mfma_f32_16x16x32_bf16 v[6:9], v[176:179], v[216:219], v[6:9]
	v_mfma_f32_16x16x32_bf16 v[6:9], v[180:183], v[220:223], v[6:9]
	v_mfma_f32_16x16x32_bf16 v[2:5], v[184:187], v[216:219], v[2:5]
	v_mfma_f32_16x16x32_bf16 v[2:5], v[188:191], v[220:223], v[2:5]
	s_barrier
	s_add_i32 s30, s30, 2
	s_add_u32 s0, s0, 0x100
	s_addc_u32 s1, s1, 0
	s_add_u32 s27, s27, 0x100
	s_addc_u32 s29, s29, 0
	s_cmp_gt_u32 s30, 61
	s_cbranch_scc0 .LBB0_216
	s_and_b64 vcc, exec, s[10:11]
	s_cbranch_vccz .LBB0_219
	s_barrier

.LBB0_270:
	s_ashr_i32 s13, s12, 31
	s_lshl_b64 s[14:15], s[12:13], 20
	s_add_u32 s14, s79, s14
	s_addc_u32 s15, s93, s15
	s_and_b64 s[16:17], s[2:3], exec
	s_cselect_b32 s13, s15, s21
	s_cselect_b32 s25, s14, s20
	s_ashr_i32 s11, s10, 31
	s_lshl_b64 s[16:17], s[10:11], 20
	s_add_u32 s16, s76, s16
	s_addc_u32 s17, s77, s17
	s_and_b64 s[22:23], s[2:3], exec
	s_cselect_b32 s11, s17, s1
	s_cselect_b32 s26, s16, s0
	s_add_u32 s20, s20, 0x80080
	s_addc_u32 s21, s21, 0
	s_add_u32 s27, s0, 0x100
	v_mov_b32_e32 v34, 0
	v_mov_b32_e32 v173, v163
	v_mov_b32_e32 v169, v163
	v_mov_b32_e32 v171, v163
	s_addc_u32 s28, s1, 0
	s_mov_b32 s29, -2
	v_mov_b64_e32 v[34:35], 0
	v_mov_b64_e32 v[36:37], 0
	v_mov_b64_e32 v[38:39], 0
	v_mov_b64_e32 v[40:41], 0
	v_mov_b64_e32 v[42:43], 0
	v_mov_b64_e32 v[44:45], 0
	v_mov_b64_e32 v[46:47], 0
	v_mov_b64_e32 v[48:49], 0
	v_mov_b64_e32 v[50:51], 0
	v_mov_b64_e32 v[52:53], 0
	v_mov_b64_e32 v[54:55], 0
	v_mov_b64_e32 v[56:57], 0
	v_mov_b64_e32 v[58:59], 0
	v_mov_b64_e32 v[60:61], 0
	v_mov_b64_e32 v[62:63], 0
	v_mov_b64_e32 v[64:65], 0
	v_mov_b64_e32 v[66:67], 0
	v_mov_b64_e32 v[68:69], 0
	v_mov_b64_e32 v[70:71], 0
	v_mov_b64_e32 v[72:73], 0
	v_mov_b64_e32 v[74:75], 0
	v_mov_b64_e32 v[76:77], 0
	v_mov_b64_e32 v[78:79], 0
	v_mov_b64_e32 v[80:81], 0
	v_mov_b64_e32 v[82:83], 0
	v_mov_b64_e32 v[84:85], 0
	v_mov_b64_e32 v[86:87], 0
	v_mov_b64_e32 v[88:89], 0
	v_mov_b64_e32 v[90:91], 0
	v_mov_b64_e32 v[92:93], 0
	v_mov_b64_e32 v[94:95], 0
	v_mov_b64_e32 v[96:97], 0
	v_mov_b64_e32 v[98:99], 0
	v_mov_b64_e32 v[100:101], 0
	v_mov_b64_e32 v[102:103], 0
	v_mov_b64_e32 v[104:105], 0
	v_mov_b64_e32 v[106:107], 0
	v_mov_b64_e32 v[108:109], 0
	v_mov_b64_e32 v[110:111], 0
	v_mov_b64_e32 v[112:113], 0
	v_mov_b64_e32 v[114:115], 0
	v_mov_b64_e32 v[116:117], 0
	v_mov_b64_e32 v[118:119], 0
	v_mov_b64_e32 v[120:121], 0
	v_mov_b64_e32 v[122:123], 0
	v_mov_b64_e32 v[124:125], 0
	v_mov_b64_e32 v[126:127], 0
	v_mov_b64_e32 v[128:129], 0
	v_mov_b64_e32 v[130:131], 0
	v_mov_b64_e32 v[132:133], 0
	v_mov_b64_e32 v[134:135], 0
	v_mov_b64_e32 v[136:137], 0
	v_mov_b64_e32 v[138:139], 0
	v_mov_b64_e32 v[140:141], 0
	v_mov_b64_e32 v[142:143], 0
	v_mov_b64_e32 v[144:145], 0
	v_mov_b64_e32 v[146:147], 0
	v_mov_b64_e32 v[148:149], 0
	v_mov_b64_e32 v[150:151], 0
	v_mov_b64_e32 v[152:153], 0
	v_mov_b64_e32 v[154:155], 0
	v_mov_b64_e32 v[156:157], 0
	v_mov_b64_e32 v[158:159], 0
	v_mov_b64_e32 v[160:161], 0
	v_add_u32_e32 v246, 0x18000, v182
	v_add_u32_e32 v247, 0x1c000, v182
	v_cmp_gt_u32_e32 vcc, 0x100, v0
.LBB0_271:
	ds_read_b128 v[26:29], v183
	ds_read_b128 v[30:33], v183 offset:1024
	ds_read_b128 v[18:21], v183 offset:2048
	ds_read_b128 v[22:25], v183 offset:3072
	ds_read_b128 v[10:13], v184
	ds_read_b128 v[14:17], v184 offset:1024
	ds_read_b128 v[2:5], v184 offset:2048
	ds_read_b128 v[6:9], v184 offset:3072
	s_add_u32 s0, s20, 0xfff80080
	s_addc_u32 s1, s21, -1
	s_cmp_eq_u32 s29, 28
	s_cselect_b32 s23, s13, s1
	s_cselect_b32 s22, s25, s0
	s_cselect_b32 s1, s11, s28
	s_cselect_b32 s0, s26, s27
	s_add_i32 m0, s19, 0xc000
	ds_read_b128 v[174:177], v185
	ds_read_b128 v[178:181], v185 offset:1024
	ds_read_b128 v[188:191], v185 offset:2048
	ds_read_b128 v[192:195], v185 offset:3072
	ds_read_b128 v[196:199], v185 offset:4096
	ds_read_b128 v[200:203], v185 offset:5120
	ds_read_b128 v[204:207], v185 offset:6144
	ds_read_b128 v[208:211], v185 offset:7168
	global_load_lds_dwordx4 v162, s[20:21]
	s_add_i32 m0, s19, 0xe000
	s_nop 0
	global_load_lds_dwordx4 v172, s[20:21]
	s_waitcnt vmcnt(8)
	s_cbranch_vccnz .Ldefl_271_0
	s_waitcnt lgkmcnt(0)
.Ldefl_271_0:
	s_barrier
	s_waitcnt lgkmcnt(0)
	v_mfma_f32_16x16x128_f8f6f4 v[158:161], v[26:33], v[174:181], v[158:161]
	v_mfma_f32_16x16x128_f8f6f4 v[154:157], v[18:25], v[174:181], v[154:157]
	v_mfma_f32_16x16x128_f8f6f4 v[146:149], v[26:33], v[188:195], v[146:149]
	v_mfma_f32_16x16x128_f8f6f4 v[138:141], v[18:25], v[188:195], v[138:141]
	v_mfma_f32_16x16x128_f8f6f4 v[130:133], v[26:33], v[196:203], v[130:133]
	v_mfma_f32_16x16x128_f8f6f4 v[122:125], v[18:25], v[196:203], v[122:125]
	v_mfma_f32_16x16x128_f8f6f4 v[114:117], v[26:33], v[204:211], v[114:117]
	v_mfma_f32_16x16x128_f8f6f4 v[106:109], v[18:25], v[204:211], v[106:109]
	v_mfma_f32_16x16x128_f8f6f4 v[150:153], v[10:17], v[174:181], v[150:153]
	v_mfma_f32_16x16x128_f8f6f4 v[142:145], v[2:9], v[174:181], v[142:145]
	v_mfma_f32_16x16x128_f8f6f4 v[134:137], v[10:17], v[188:195], v[134:137]
	v_mfma_f32_16x16x128_f8f6f4 v[126:129], v[2:9], v[188:195], v[126:129]
	v_mfma_f32_16x16x128_f8f6f4 v[118:121], v[10:17], v[196:203], v[118:121]
	v_mfma_f32_16x16x128_f8f6f4 v[110:113], v[2:9], v[196:203], v[110:113]
	v_mfma_f32_16x16x128_f8f6f4 v[102:105], v[10:17], v[204:211], v[102:105]
	v_mfma_f32_16x16x128_f8f6f4 v[98:101], v[2:9], v[204:211], v[98:101]
	s_barrier
	s_add_i32 s30, s48, s37
	s_mov_b32 m0, s30
	ds_read_b128 v[188:191], v185 offset:16384
	ds_read_b128 v[192:195], v185 offset:17408
	ds_read_b128 v[196:199], v185 offset:18432
	ds_read_b128 v[200:203], v185 offset:19456
	ds_read_b128 v[204:207], v185 offset:20480
	ds_read_b128 v[208:211], v185 offset:21504
	ds_read_b128 v[212:215], v185 offset:22528
	ds_read_b128 v[216:219], v185 offset:23552
	global_load_lds_dwordx4 v168, s[0:1]
	s_add_i32 m0, s30, 0x2000
	s_add_u32 s30, s0, 0x80000
	s_addc_u32 s31, s1, 0
	s_add_i32 s33, s49, s37
	global_load_lds_dwordx4 v170, s[0:1]
	s_mov_b32 m0, s33
	global_load_lds_dwordx4 v168, s[30:31]
	s_add_i32 m0, s33, 0x2000
	s_nop 0
	global_load_lds_dwordx4 v170, s[30:31]
	s_mov_b32 m0, s19
	s_nop 0
	global_load_lds_dwordx4 v162, s[22:23]
	s_mov_b32 m0, s38
	s_nop 0
	global_load_lds_dwordx4 v172, s[22:23]
	s_waitcnt vmcnt(8)
	s_cbranch_vccnz .Ldefl_271_1
	s_waitcnt lgkmcnt(0)
.Ldefl_271_1:
	s_barrier
	s_waitcnt lgkmcnt(0)
	v_mfma_f32_16x16x128_f8f6f4 v[94:97], v[26:33], v[188:195], v[94:97]
	v_mfma_f32_16x16x128_f8f6f4 v[90:93], v[18:25], v[188:195], v[90:93]
	v_mfma_f32_16x16x128_f8f6f4 v[78:81], v[26:33], v[196:203], v[78:81]
	v_mfma_f32_16x16x128_f8f6f4 v[74:77], v[18:25], v[196:203], v[74:77]
	v_mfma_f32_16x16x128_f8f6f4 v[62:65], v[26:33], v[204:211], v[62:65]
	v_mfma_f32_16x16x128_f8f6f4 v[58:61], v[18:25], v[204:211], v[58:61]
	v_mfma_f32_16x16x128_f8f6f4 v[46:49], v[26:33], v[212:219], v[46:49]
	v_mfma_f32_16x16x128_f8f6f4 v[42:45], v[18:25], v[212:219], v[42:45]
	v_mfma_f32_16x16x128_f8f6f4 v[86:89], v[10:17], v[188:195], v[86:89]
	v_mfma_f32_16x16x128_f8f6f4 v[82:85], v[2:9], v[188:195], v[82:85]
	v_mfma_f32_16x16x128_f8f6f4 v[70:73], v[10:17], v[196:203], v[70:73]
	v_mfma_f32_16x16x128_f8f6f4 v[66:69], v[2:9], v[196:203], v[66:69]
	v_mfma_f32_16x16x128_f8f6f4 v[54:57], v[10:17], v[204:211], v[54:57]
	v_mfma_f32_16x16x128_f8f6f4 v[50:53], v[2:9], v[204:211], v[50:53]
	v_mfma_f32_16x16x128_f8f6f4 v[38:41], v[10:17], v[212:219], v[38:41]
	v_mfma_f32_16x16x128_f8f6f4 v[34:37], v[2:9], v[212:219], v[34:37]
	s_barrier
	s_add_i32 s30, 0, 0x18000
	s_add_i32 s31, 0, 0x1c000
	ds_read_b128 v[2:5], v246
	ds_read_b128 v[6:9], v246 offset:1024
	ds_read_b128 v[10:13], v246 offset:2048
	ds_read_b128 v[14:17], v246 offset:3072
	ds_read_b128 v[18:21], v247
	ds_read_b128 v[22:25], v247 offset:1024
	ds_read_b128 v[26:29], v247 offset:2048
	ds_read_b128 v[30:33], v247 offset:3072
	s_add_u32 s98, s22, 0x80
	s_addc_u32 s99, s23, 0
	s_add_u32 s22, s22, 0x80000
	s_addc_u32 s23, s23, 0
	s_mov_b32 m0, s39
	ds_read_b128 v[188:191], v185 offset:32768
	ds_read_b128 v[192:195], v185 offset:33792
	ds_read_b128 v[196:199], v185 offset:34816
	ds_read_b128 v[200:203], v185 offset:35840
	ds_read_b128 v[204:207], v185 offset:36864
	ds_read_b128 v[208:211], v185 offset:37888
	ds_read_b128 v[212:215], v185 offset:38912
	ds_read_b128 v[216:219], v185 offset:39936
	global_load_lds_dwordx4 v162, s[22:23]
	s_mov_b32 m0, s40
	s_nop 0
	global_load_lds_dwordx4 v172, s[22:23]
	s_waitcnt vmcnt(8)
	s_cbranch_vccnz .Ldefl_271_2
	s_waitcnt lgkmcnt(0)
.Ldefl_271_2:
	s_barrier
	s_waitcnt lgkmcnt(0)
	v_mfma_f32_16x16x128_f8f6f4 v[158:161], v[2:9], v[188:195], v[158:161]
	v_mfma_f32_16x16x128_f8f6f4 v[154:157], v[10:17], v[188:195], v[154:157]
	v_mfma_f32_16x16x128_f8f6f4 v[146:149], v[2:9], v[196:203], v[146:149]
	v_mfma_f32_16x16x128_f8f6f4 v[138:141], v[10:17], v[196:203], v[138:141]
	v_mfma_f32_16x16x128_f8f6f4 v[130:133], v[2:9], v[204:211], v[130:133]
	v_mfma_f32_16x16x128_f8f6f4 v[122:125], v[10:17], v[204:211], v[122:125]
	v_mfma_f32_16x16x128_f8f6f4 v[114:117], v[2:9], v[212:219], v[114:117]
	v_mfma_f32_16x16x128_f8f6f4 v[106:109], v[10:17], v[212:219], v[106:109]
	v_mfma_f32_16x16x128_f8f6f4 v[150:153], v[18:25], v[188:195], v[150:153]
	v_mfma_f32_16x16x128_f8f6f4 v[142:145], v[26:33], v[188:195], v[142:145]
	v_mfma_f32_16x16x128_f8f6f4 v[134:137], v[18:25], v[196:203], v[134:137]
	v_mfma_f32_16x16x128_f8f6f4 v[126:129], v[26:33], v[196:203], v[126:129]
	v_mfma_f32_16x16x128_f8f6f4 v[118:121], v[18:25], v[204:211], v[118:121]
	v_mfma_f32_16x16x128_f8f6f4 v[110:113], v[26:33], v[204:211], v[110:113]
	v_mfma_f32_16x16x128_f8f6f4 v[102:105], v[18:25], v[212:219], v[102:105]
	v_mfma_f32_16x16x128_f8f6f4 v[98:101], v[26:33], v[212:219], v[98:101]
	s_barrier
	s_add_i32 s22, s30, s37
	s_mov_b32 m0, s22
	ds_read_b128 v[188:191], v185 offset:49152
	ds_read_b128 v[192:195], v185 offset:50176
	ds_read_b128 v[196:199], v185 offset:51200
	ds_read_b128 v[200:203], v185 offset:52224
	ds_read_b128 v[204:207], v185 offset:53248
	ds_read_b128 v[208:211], v185 offset:54272
	ds_read_b128 v[212:215], v185 offset:55296
	ds_read_b128 v[216:219], v185 offset:56320
	s_add_u32 s0, s0, 0x80
	s_addc_u32 s1, s1, 0
	global_load_lds_dwordx4 v168, s[0:1]
	s_add_i32 m0, s22, 0x2000
	s_add_i32 s22, s31, s37
	global_load_lds_dwordx4 v170, s[0:1]
	s_add_u32 s0, s0, 0x80000
	s_addc_u32 s1, s1, 0
	s_mov_b32 m0, s22
	s_nop 0
	global_load_lds_dwordx4 v168, s[0:1]
	s_add_i32 m0, s22, 0x2000
	s_nop 0
	global_load_lds_dwordx4 v170, s[0:1]
	s_mov_b32 m0, s44
	s_nop 0
	global_load_lds_dwordx4 v162, s[98:99]
	s_mov_b32 m0, s45
	s_nop 0
	global_load_lds_dwordx4 v172, s[98:99]
	s_waitcnt vmcnt(8)
	s_cbranch_vccnz .Ldefl_271_3
	s_waitcnt lgkmcnt(0)
.Ldefl_271_3:
	s_barrier
	s_waitcnt lgkmcnt(0)
	v_mfma_f32_16x16x128_f8f6f4 v[94:97], v[2:9], v[188:195], v[94:97]
	v_mfma_f32_16x16x128_f8f6f4 v[90:93], v[10:17], v[188:195], v[90:93]
	v_mfma_f32_16x16x128_f8f6f4 v[78:81], v[2:9], v[196:203], v[78:81]
	v_mfma_f32_16x16x128_f8f6f4 v[74:77], v[10:17], v[196:203], v[74:77]
	v_mfma_f32_16x16x128_f8f6f4 v[62:65], v[2:9], v[204:211], v[62:65]
	v_mfma_f32_16x16x128_f8f6f4 v[58:61], v[10:17], v[204:211], v[58:61]
	v_mfma_f32_16x16x128_f8f6f4 v[46:49], v[2:9], v[212:219], v[46:49]
	v_mfma_f32_16x16x128_f8f6f4 v[42:45], v[10:17], v[212:219], v[42:45]
	v_mfma_f32_16x16x128_f8f6f4 v[86:89], v[18:25], v[188:195], v[86:89]
	v_mfma_f32_16x16x128_f8f6f4 v[82:85], v[26:33], v[188:195], v[82:85]
	v_mfma_f32_16x16x128_f8f6f4 v[70:73], v[18:25], v[196:203], v[70:73]
	v_mfma_f32_16x16x128_f8f6f4 v[66:69], v[26:33], v[196:203], v[66:69]
	v_mfma_f32_16x16x128_f8f6f4 v[54:57], v[18:25], v[204:211], v[54:57]
	v_mfma_f32_16x16x128_f8f6f4 v[50:53], v[26:33], v[204:211], v[50:53]
	v_mfma_f32_16x16x128_f8f6f4 v[38:41], v[18:25], v[212:219], v[38:41]
	v_mfma_f32_16x16x128_f8f6f4 v[34:37], v[26:33], v[212:219], v[34:37]
	s_barrier
	s_add_i32 s29, s29, 2
	s_add_u32 s20, s20, 0x100
	s_addc_u32 s21, s21, 0
	s_add_u32 s27, s27, 0x100
	s_addc_u32 s28, s28, 0
	s_cmp_gt_u32 s29, 29
	s_cbranch_scc0 .LBB0_271
	s_and_b64 vcc, exec, s[8:9]
	s_cbranch_vccz .LBB0_274
	s_barrier

.LBB0_838:
	s_ashr_i32 s21, s20, 31
	s_lshl_b64 s[22:23], s[20:21], 19
	s_add_u32 s22, s68, s22
	s_addc_u32 s23, s69, s23
	s_and_b64 s[24:25], s[2:3], exec
	s_cselect_b32 s21, s23, s29
	s_cselect_b32 s49, s22, s28
	s_ashr_i32 s19, s18, 31
	s_lshl_b64 s[24:25], s[18:19], 19
	v_readlane_b32 s34, v245, 14
	v_readlane_b32 s35, v245, 15
	s_add_u32 s24, s34, s24
	s_addc_u32 s25, s35, s25
	s_and_b64 s[34:35], s[2:3], exec
	s_cselect_b32 s19, s25, s31
	s_cselect_b32 s50, s24, s30
	s_add_u32 s28, s28, 0x40080
	s_addc_u32 s29, s29, 0
	s_add_u32 s51, s30, 0x100
	v_mov_b32_e32 v34, 0
	v_mov_b32_e32 v173, v163
	v_mov_b32_e32 v169, v163
	v_mov_b32_e32 v171, v163
	s_addc_u32 s52, s31, 0
	s_mov_b32 s53, -2
	v_mov_b64_e32 v[34:35], 0
	v_mov_b64_e32 v[36:37], 0
	v_mov_b64_e32 v[38:39], 0
	v_mov_b64_e32 v[40:41], 0
	v_mov_b64_e32 v[42:43], 0
	v_mov_b64_e32 v[44:45], 0
	v_mov_b64_e32 v[46:47], 0
	v_mov_b64_e32 v[48:49], 0
	v_mov_b64_e32 v[50:51], 0
	v_mov_b64_e32 v[52:53], 0
	v_mov_b64_e32 v[54:55], 0
	v_mov_b64_e32 v[56:57], 0
	v_mov_b64_e32 v[58:59], 0
	v_mov_b64_e32 v[60:61], 0
	v_mov_b64_e32 v[62:63], 0
	v_mov_b64_e32 v[64:65], 0
	v_mov_b64_e32 v[66:67], 0
	v_mov_b64_e32 v[68:69], 0
	v_mov_b64_e32 v[70:71], 0
	v_mov_b64_e32 v[72:73], 0
	v_mov_b64_e32 v[74:75], 0
	v_mov_b64_e32 v[76:77], 0
	v_mov_b64_e32 v[78:79], 0
	v_mov_b64_e32 v[80:81], 0
	v_mov_b64_e32 v[82:83], 0
	v_mov_b64_e32 v[84:85], 0
	v_mov_b64_e32 v[86:87], 0
	v_mov_b64_e32 v[88:89], 0
	v_mov_b64_e32 v[90:91], 0
	v_mov_b64_e32 v[92:93], 0
	v_mov_b64_e32 v[94:95], 0
	v_mov_b64_e32 v[96:97], 0
	s_waitcnt vmcnt(0)
	v_mov_b64_e32 v[98:99], 0
	v_mov_b64_e32 v[100:101], 0
	v_mov_b64_e32 v[102:103], 0
	v_mov_b64_e32 v[104:105], 0
	v_mov_b64_e32 v[106:107], 0
	v_mov_b64_e32 v[108:109], 0
	v_mov_b64_e32 v[110:111], 0
	v_mov_b64_e32 v[112:113], 0
	v_mov_b64_e32 v[114:115], 0
	v_mov_b64_e32 v[116:117], 0
	v_mov_b64_e32 v[118:119], 0
	v_mov_b64_e32 v[120:121], 0
	v_mov_b64_e32 v[122:123], 0
	v_mov_b64_e32 v[124:125], 0
	v_mov_b64_e32 v[126:127], 0
	v_mov_b64_e32 v[128:129], 0
	v_mov_b64_e32 v[130:131], 0
	v_mov_b64_e32 v[132:133], 0
	v_mov_b64_e32 v[134:135], 0
	v_mov_b64_e32 v[136:137], 0
	v_mov_b64_e32 v[138:139], 0
	v_mov_b64_e32 v[140:141], 0
	v_mov_b64_e32 v[142:143], 0
	v_mov_b64_e32 v[144:145], 0
	v_mov_b64_e32 v[146:147], 0
	v_mov_b64_e32 v[148:149], 0
	v_mov_b64_e32 v[150:151], 0
	v_mov_b64_e32 v[152:153], 0
	v_mov_b64_e32 v[154:155], 0
	v_mov_b64_e32 v[156:157], 0
	v_mov_b64_e32 v[158:159], 0
	v_mov_b64_e32 v[160:161], 0
	v_add_u32_e32 v246, 0x18000, v182
	v_add_u32_e32 v247, 0x1c000, v182
	v_cmp_gt_u32_e32 vcc, 0x100, v0
.LBB0_839:
	ds_read_b128 v[26:29], v183
	ds_read_b128 v[30:33], v183 offset:1024
	ds_read_b128 v[18:21], v183 offset:2048
	ds_read_b128 v[22:25], v183 offset:3072
	ds_read_b128 v[10:13], v184
	ds_read_b128 v[14:17], v184 offset:1024
	ds_read_b128 v[2:5], v184 offset:2048
	ds_read_b128 v[6:9], v184 offset:3072
	s_add_u32 s30, s28, 0xfffc0080
	s_addc_u32 s31, s29, -1
	s_cmp_eq_u32 s53, 12
	s_cselect_b32 s35, s21, s31
	s_cselect_b32 s34, s49, s30
	s_cselect_b32 s31, s19, s52
	s_cselect_b32 s30, s50, s51
	s_add_i32 m0, s27, 0xc000
	ds_read_b128 v[174:177], v185
	ds_read_b128 v[178:181], v185 offset:1024
	ds_read_b128 v[188:191], v185 offset:2048
	ds_read_b128 v[192:195], v185 offset:3072
	ds_read_b128 v[196:199], v185 offset:4096
	ds_read_b128 v[200:203], v185 offset:5120
	ds_read_b128 v[204:207], v185 offset:6144
	ds_read_b128 v[208:211], v185 offset:7168
	global_load_lds_dwordx4 v162, s[28:29]
	s_add_i32 m0, s27, 0xe000
	s_nop 0
	global_load_lds_dwordx4 v172, s[28:29]
	s_waitcnt vmcnt(8)
	s_cbranch_vccnz .Ldefl_839_0
	s_waitcnt lgkmcnt(0)
.Ldefl_839_0:
	s_barrier
	s_waitcnt lgkmcnt(0)
	v_mfma_f32_16x16x128_f8f6f4 v[158:161], v[26:33], v[174:181], v[158:161]
	v_mfma_f32_16x16x128_f8f6f4 v[154:157], v[18:25], v[174:181], v[154:157]
	v_mfma_f32_16x16x128_f8f6f4 v[142:145], v[26:33], v[188:195], v[142:145]
	v_mfma_f32_16x16x128_f8f6f4 v[138:141], v[18:25], v[188:195], v[138:141]
	v_mfma_f32_16x16x128_f8f6f4 v[126:129], v[26:33], v[196:203], v[126:129]
	v_mfma_f32_16x16x128_f8f6f4 v[122:125], v[18:25], v[196:203], v[122:125]
	v_mfma_f32_16x16x128_f8f6f4 v[110:113], v[26:33], v[204:211], v[110:113]
	v_mfma_f32_16x16x128_f8f6f4 v[106:109], v[18:25], v[204:211], v[106:109]
	v_mfma_f32_16x16x128_f8f6f4 v[150:153], v[10:17], v[174:181], v[150:153]
	v_mfma_f32_16x16x128_f8f6f4 v[146:149], v[2:9], v[174:181], v[146:149]
	v_mfma_f32_16x16x128_f8f6f4 v[134:137], v[10:17], v[188:195], v[134:137]
	v_mfma_f32_16x16x128_f8f6f4 v[130:133], v[2:9], v[188:195], v[130:133]
	v_mfma_f32_16x16x128_f8f6f4 v[118:121], v[10:17], v[196:203], v[118:121]
	v_mfma_f32_16x16x128_f8f6f4 v[114:117], v[2:9], v[196:203], v[114:117]
	v_mfma_f32_16x16x128_f8f6f4 v[102:105], v[10:17], v[204:211], v[102:105]
	v_mfma_f32_16x16x128_f8f6f4 v[98:101], v[2:9], v[204:211], v[98:101]
	s_barrier
	s_add_i32 s54, s46, s36
	s_mov_b32 m0, s54
	ds_read_b128 v[188:191], v185 offset:16384
	ds_read_b128 v[192:195], v185 offset:17408
	ds_read_b128 v[196:199], v185 offset:18432
	ds_read_b128 v[200:203], v185 offset:19456
	ds_read_b128 v[204:207], v185 offset:20480
	ds_read_b128 v[208:211], v185 offset:21504
	ds_read_b128 v[212:215], v185 offset:22528
	ds_read_b128 v[216:219], v185 offset:23552
	global_load_lds_dwordx4 v168, s[30:31]
	s_add_i32 m0, s54, 0x2000
	s_add_u32 s54, s30, 0x40000
	s_addc_u32 s55, s31, 0
	s_add_i32 s56, s47, s36
	global_load_lds_dwordx4 v170, s[30:31]
	s_mov_b32 m0, s56
	global_load_lds_dwordx4 v168, s[54:55]
	s_add_i32 m0, s56, 0x2000
	s_nop 0
	global_load_lds_dwordx4 v170, s[54:55]
	s_mov_b32 m0, s27
	s_nop 0
	global_load_lds_dwordx4 v162, s[34:35]
	s_mov_b32 m0, s37
	s_nop 0
	global_load_lds_dwordx4 v172, s[34:35]
	s_waitcnt vmcnt(8)
	s_cbranch_vccnz .Ldefl_839_1
	s_waitcnt lgkmcnt(0)
.Ldefl_839_1:
	s_barrier
	s_waitcnt lgkmcnt(0)
	v_mfma_f32_16x16x128_f8f6f4 v[94:97], v[26:33], v[188:195], v[94:97]
	v_mfma_f32_16x16x128_f8f6f4 v[90:93], v[18:25], v[188:195], v[90:93]
	v_mfma_f32_16x16x128_f8f6f4 v[78:81], v[26:33], v[196:203], v[78:81]
	v_mfma_f32_16x16x128_f8f6f4 v[74:77], v[18:25], v[196:203], v[74:77]
	v_mfma_f32_16x16x128_f8f6f4 v[62:65], v[26:33], v[204:211], v[62:65]
	v_mfma_f32_16x16x128_f8f6f4 v[58:61], v[18:25], v[204:211], v[58:61]
	v_mfma_f32_16x16x128_f8f6f4 v[46:49], v[26:33], v[212:219], v[46:49]
	v_mfma_f32_16x16x128_f8f6f4 v[42:45], v[18:25], v[212:219], v[42:45]
	v_mfma_f32_16x16x128_f8f6f4 v[86:89], v[10:17], v[188:195], v[86:89]
	v_mfma_f32_16x16x128_f8f6f4 v[82:85], v[2:9], v[188:195], v[82:85]
	v_mfma_f32_16x16x128_f8f6f4 v[70:73], v[10:17], v[196:203], v[70:73]
	v_mfma_f32_16x16x128_f8f6f4 v[66:69], v[2:9], v[196:203], v[66:69]
	v_mfma_f32_16x16x128_f8f6f4 v[54:57], v[10:17], v[204:211], v[54:57]
	v_mfma_f32_16x16x128_f8f6f4 v[50:53], v[2:9], v[204:211], v[50:53]
	v_mfma_f32_16x16x128_f8f6f4 v[38:41], v[10:17], v[212:219], v[38:41]
	v_mfma_f32_16x16x128_f8f6f4 v[34:37], v[2:9], v[212:219], v[34:37]
	s_barrier
	s_add_i32 s54, 0, 0x18000
	s_add_i32 s55, 0, 0x1c000
	ds_read_b128 v[2:5], v246
	ds_read_b128 v[6:9], v246 offset:1024
	ds_read_b128 v[10:13], v246 offset:2048
	ds_read_b128 v[14:17], v246 offset:3072
	ds_read_b128 v[18:21], v247
	ds_read_b128 v[22:25], v247 offset:1024
	ds_read_b128 v[26:29], v247 offset:2048
	ds_read_b128 v[30:33], v247 offset:3072
	s_add_u32 s98, s34, 0x80
	s_addc_u32 s99, s35, 0
	s_add_u32 s34, s34, 0x40000
	s_addc_u32 s35, s35, 0
	s_mov_b32 m0, s38
	ds_read_b128 v[188:191], v185 offset:32768
	ds_read_b128 v[192:195], v185 offset:33792
	ds_read_b128 v[196:199], v185 offset:34816
	ds_read_b128 v[200:203], v185 offset:35840
	ds_read_b128 v[204:207], v185 offset:36864
	ds_read_b128 v[208:211], v185 offset:37888
	ds_read_b128 v[212:215], v185 offset:38912
	ds_read_b128 v[216:219], v185 offset:39936
	global_load_lds_dwordx4 v162, s[34:35]
	s_mov_b32 m0, s39
	s_nop 0
	global_load_lds_dwordx4 v172, s[34:35]
	s_waitcnt vmcnt(8)
	s_cbranch_vccnz .Ldefl_839_2
	s_waitcnt lgkmcnt(0)
.Ldefl_839_2:
	s_barrier
	s_waitcnt lgkmcnt(0)
	v_mfma_f32_16x16x128_f8f6f4 v[158:161], v[2:9], v[188:195], v[158:161]
	v_mfma_f32_16x16x128_f8f6f4 v[154:157], v[10:17], v[188:195], v[154:157]
	v_mfma_f32_16x16x128_f8f6f4 v[142:145], v[2:9], v[196:203], v[142:145]
	v_mfma_f32_16x16x128_f8f6f4 v[138:141], v[10:17], v[196:203], v[138:141]
	v_mfma_f32_16x16x128_f8f6f4 v[126:129], v[2:9], v[204:211], v[126:129]
	v_mfma_f32_16x16x128_f8f6f4 v[122:125], v[10:17], v[204:211], v[122:125]
	v_mfma_f32_16x16x128_f8f6f4 v[110:113], v[2:9], v[212:219], v[110:113]
	v_mfma_f32_16x16x128_f8f6f4 v[106:109], v[10:17], v[212:219], v[106:109]
	v_mfma_f32_16x16x128_f8f6f4 v[150:153], v[18:25], v[188:195], v[150:153]
	v_mfma_f32_16x16x128_f8f6f4 v[146:149], v[26:33], v[188:195], v[146:149]
	v_mfma_f32_16x16x128_f8f6f4 v[134:137], v[18:25], v[196:203], v[134:137]
	v_mfma_f32_16x16x128_f8f6f4 v[130:133], v[26:33], v[196:203], v[130:133]
	v_mfma_f32_16x16x128_f8f6f4 v[118:121], v[18:25], v[204:211], v[118:121]
	v_mfma_f32_16x16x128_f8f6f4 v[114:117], v[26:33], v[204:211], v[114:117]
	v_mfma_f32_16x16x128_f8f6f4 v[102:105], v[18:25], v[212:219], v[102:105]
	v_mfma_f32_16x16x128_f8f6f4 v[98:101], v[26:33], v[212:219], v[98:101]
	s_barrier
	s_add_i32 s34, s54, s36
	s_mov_b32 m0, s34
	ds_read_b128 v[188:191], v185 offset:49152
	ds_read_b128 v[192:195], v185 offset:50176
	ds_read_b128 v[196:199], v185 offset:51200
	ds_read_b128 v[200:203], v185 offset:52224
	ds_read_b128 v[204:207], v185 offset:53248
	ds_read_b128 v[208:211], v185 offset:54272
	ds_read_b128 v[212:215], v185 offset:55296
	ds_read_b128 v[216:219], v185 offset:56320
	s_add_u32 s30, s30, 0x80
	s_addc_u32 s31, s31, 0
	global_load_lds_dwordx4 v168, s[30:31]
	s_add_i32 m0, s34, 0x2000
	s_add_i32 s34, s55, s36
	global_load_lds_dwordx4 v170, s[30:31]
	s_add_u32 s30, s30, 0x40000
	s_addc_u32 s31, s31, 0
	s_mov_b32 m0, s34
	s_nop 0
	global_load_lds_dwordx4 v168, s[30:31]
	s_add_i32 m0, s34, 0x2000
	s_nop 0
	global_load_lds_dwordx4 v170, s[30:31]
	s_mov_b32 m0, s43
	s_nop 0
	global_load_lds_dwordx4 v162, s[98:99]
	s_mov_b32 m0, s44
	s_nop 0
	global_load_lds_dwordx4 v172, s[98:99]
	s_waitcnt vmcnt(8)
	s_cbranch_vccnz .Ldefl_839_3
	s_waitcnt lgkmcnt(0)
.Ldefl_839_3:
	s_barrier
	s_waitcnt lgkmcnt(0)
	v_mfma_f32_16x16x128_f8f6f4 v[94:97], v[2:9], v[188:195], v[94:97]
	v_mfma_f32_16x16x128_f8f6f4 v[90:93], v[10:17], v[188:195], v[90:93]
	v_mfma_f32_16x16x128_f8f6f4 v[78:81], v[2:9], v[196:203], v[78:81]
	v_mfma_f32_16x16x128_f8f6f4 v[74:77], v[10:17], v[196:203], v[74:77]
	v_mfma_f32_16x16x128_f8f6f4 v[62:65], v[2:9], v[204:211], v[62:65]
	v_mfma_f32_16x16x128_f8f6f4 v[58:61], v[10:17], v[204:211], v[58:61]
	v_mfma_f32_16x16x128_f8f6f4 v[46:49], v[2:9], v[212:219], v[46:49]
	v_mfma_f32_16x16x128_f8f6f4 v[42:45], v[10:17], v[212:219], v[42:45]
	v_mfma_f32_16x16x128_f8f6f4 v[86:89], v[18:25], v[188:195], v[86:89]
	v_mfma_f32_16x16x128_f8f6f4 v[82:85], v[26:33], v[188:195], v[82:85]
	v_mfma_f32_16x16x128_f8f6f4 v[70:73], v[18:25], v[196:203], v[70:73]
	v_mfma_f32_16x16x128_f8f6f4 v[66:69], v[26:33], v[196:203], v[66:69]
	v_mfma_f32_16x16x128_f8f6f4 v[54:57], v[18:25], v[204:211], v[54:57]
	v_mfma_f32_16x16x128_f8f6f4 v[50:53], v[26:33], v[204:211], v[50:53]
	v_mfma_f32_16x16x128_f8f6f4 v[38:41], v[18:25], v[212:219], v[38:41]
	v_mfma_f32_16x16x128_f8f6f4 v[34:37], v[26:33], v[212:219], v[34:37]
	s_barrier
	s_add_i32 s53, s53, 2
	s_add_u32 s28, s28, 0x100
	s_addc_u32 s29, s29, 0
	s_add_u32 s51, s51, 0x100
	s_addc_u32 s52, s52, 0
	s_cmp_gt_u32 s53, 13
	s_cbranch_scc0 .LBB0_839
	s_and_b64 vcc, exec, s[10:11]
	s_cbranch_vccz .LBB0_842
	s_barrier

.LBB0_862:
	s_ashr_i32 s13, s12, 31
	s_lshl_b64 s[14:15], s[12:13], 20
	s_add_u32 s14, s62, s14
	s_addc_u32 s15, s63, s15
	s_and_b64 s[16:17], s[2:3], exec
	s_cselect_b32 s13, s15, s21
	s_cselect_b32 s39, s14, s20
	s_ashr_i32 s11, s10, 31
	s_lshl_b64 s[16:17], s[10:11], 20
	v_readlane_b32 s24, v245, 16
	v_readlane_b32 s25, v245, 17
	s_add_u32 s16, s24, s16
	s_addc_u32 s17, s25, s17
	s_and_b64 s[24:25], s[2:3], exec
	s_cselect_b32 s11, s17, s23
	s_cselect_b32 s40, s16, s22
	s_add_u32 s20, s20, 0x80080
	s_addc_u32 s21, s21, 0
	s_add_u32 s41, s22, 0x100
	v_mov_b32_e32 v2, 0
	s_addc_u32 s42, s23, 0
	s_mov_b32 s43, -2
	v_mov_b64_e32 v[2:3], 0
	v_mov_b64_e32 v[4:5], 0
	v_mov_b64_e32 v[6:7], 0
	v_mov_b64_e32 v[8:9], 0
	v_mov_b64_e32 v[10:11], 0
	v_mov_b64_e32 v[12:13], 0
	v_mov_b64_e32 v[14:15], 0
	v_mov_b64_e32 v[16:17], 0
	v_mov_b64_e32 v[18:19], 0
	v_mov_b64_e32 v[20:21], 0
	v_mov_b64_e32 v[22:23], 0
	v_mov_b64_e32 v[24:25], 0
	v_mov_b64_e32 v[26:27], 0
	v_mov_b64_e32 v[28:29], 0
	v_mov_b64_e32 v[30:31], 0
	v_mov_b64_e32 v[32:33], 0
	v_mov_b64_e32 v[34:35], 0
	v_mov_b64_e32 v[36:37], 0
	v_mov_b64_e32 v[38:39], 0
	v_mov_b64_e32 v[40:41], 0
	v_mov_b64_e32 v[42:43], 0
	v_mov_b64_e32 v[44:45], 0
	v_mov_b64_e32 v[46:47], 0
	v_mov_b64_e32 v[48:49], 0
	v_mov_b64_e32 v[50:51], 0
	v_mov_b64_e32 v[52:53], 0
	v_mov_b64_e32 v[54:55], 0
	v_mov_b64_e32 v[56:57], 0
	v_mov_b64_e32 v[58:59], 0
	v_mov_b64_e32 v[60:61], 0
	v_mov_b64_e32 v[62:63], 0
	v_mov_b64_e32 v[64:65], 0
	v_mov_b64_e32 v[66:67], 0
	v_mov_b64_e32 v[68:69], 0
	v_mov_b64_e32 v[70:71], 0
	v_mov_b64_e32 v[72:73], 0
	v_mov_b64_e32 v[74:75], 0
	v_mov_b64_e32 v[76:77], 0
	v_mov_b64_e32 v[78:79], 0
	v_mov_b64_e32 v[80:81], 0
	v_mov_b64_e32 v[82:83], 0
	v_mov_b64_e32 v[84:85], 0
	v_mov_b64_e32 v[86:87], 0
	v_mov_b64_e32 v[88:89], 0
	v_mov_b64_e32 v[90:91], 0
	v_mov_b64_e32 v[92:93], 0
	v_mov_b64_e32 v[94:95], 0
	v_mov_b64_e32 v[96:97], 0
	v_mov_b64_e32 v[98:99], 0
	v_mov_b64_e32 v[100:101], 0
	v_mov_b64_e32 v[102:103], 0
	v_mov_b64_e32 v[104:105], 0
	v_mov_b64_e32 v[106:107], 0
	v_mov_b64_e32 v[108:109], 0
	v_mov_b64_e32 v[110:111], 0
	v_mov_b64_e32 v[112:113], 0
	v_mov_b64_e32 v[114:115], 0
	v_mov_b64_e32 v[116:117], 0
	v_mov_b64_e32 v[118:119], 0
	v_mov_b64_e32 v[120:121], 0
	v_mov_b64_e32 v[122:123], 0
	v_mov_b64_e32 v[124:125], 0
	v_mov_b64_e32 v[126:127], 0
	v_mov_b64_e32 v[128:129], 0
	v_add_u32_e32 v246, 0x18000, v152
	v_add_u32_e32 v247, 0x1c000, v152
	v_cmp_gt_u32_e32 vcc, 0x100, v0
.LBB0_863:
	ds_read_b128 v[146:149], v154
	ds_read_b128 v[158:161], v154 offset:1024
	ds_read_b128 v[162:165], v154 offset:2048
	ds_read_b128 v[166:169], v154 offset:3072
	ds_read_b128 v[170:173], v155
	ds_read_b128 v[174:177], v155 offset:1024
	ds_read_b128 v[178:181], v155 offset:2048
	ds_read_b128 v[182:185], v155 offset:3072
	s_add_u32 s22, s20, 0xfff80080
	s_addc_u32 s23, s21, -1
	s_cmp_eq_u32 s43, 28
	s_cselect_b32 s25, s13, s23
	s_cselect_b32 s24, s39, s22
	s_cselect_b32 s23, s11, s42
	s_cselect_b32 s22, s40, s41
	s_add_i32 m0, s19, 0xc000
	ds_read_b128 v[186:189], v156
	ds_read_b128 v[190:193], v156 offset:1024
	ds_read_b128 v[194:197], v156 offset:2048
	ds_read_b128 v[198:201], v156 offset:3072
	ds_read_b128 v[202:205], v156 offset:4096
	ds_read_b128 v[206:209], v156 offset:5120
	ds_read_b128 v[210:213], v156 offset:6144
	ds_read_b128 v[214:217], v156 offset:7168
	global_load_lds_dwordx4 v138, s[20:21]
	s_add_i32 m0, s19, 0xe000
	s_nop 0
	global_load_lds_dwordx4 v140, s[20:21]
	s_waitcnt vmcnt(8)
	s_cbranch_vccnz .Ldefl_863_0
	s_waitcnt lgkmcnt(0)
.Ldefl_863_0:
	s_barrier
	s_waitcnt lgkmcnt(0)
	v_mfma_f32_16x16x32_bf16 v[126:129], v[146:149], v[186:189], v[126:129]
	v_mfma_f32_16x16x32_bf16 v[126:129], v[158:161], v[190:193], v[126:129]
	v_mfma_f32_16x16x32_bf16 v[122:125], v[162:165], v[186:189], v[122:125]
	v_mfma_f32_16x16x32_bf16 v[122:125], v[166:169], v[190:193], v[122:125]
	v_mfma_f32_16x16x32_bf16 v[110:113], v[146:149], v[194:197], v[110:113]
	v_mfma_f32_16x16x32_bf16 v[110:113], v[158:161], v[198:201], v[110:113]
	v_mfma_f32_16x16x32_bf16 v[106:109], v[162:165], v[194:197], v[106:109]
	v_mfma_f32_16x16x32_bf16 v[106:109], v[166:169], v[198:201], v[106:109]
	v_mfma_f32_16x16x32_bf16 v[94:97], v[146:149], v[202:205], v[94:97]
	v_mfma_f32_16x16x32_bf16 v[94:97], v[158:161], v[206:209], v[94:97]
	v_mfma_f32_16x16x32_bf16 v[90:93], v[162:165], v[202:205], v[90:93]
	v_mfma_f32_16x16x32_bf16 v[90:93], v[166:169], v[206:209], v[90:93]
	v_mfma_f32_16x16x32_bf16 v[78:81], v[146:149], v[210:213], v[78:81]
	v_mfma_f32_16x16x32_bf16 v[78:81], v[158:161], v[214:217], v[78:81]
	v_mfma_f32_16x16x32_bf16 v[74:77], v[162:165], v[210:213], v[74:77]
	v_mfma_f32_16x16x32_bf16 v[74:77], v[166:169], v[214:217], v[74:77]
	v_mfma_f32_16x16x32_bf16 v[118:121], v[170:173], v[186:189], v[118:121]
	v_mfma_f32_16x16x32_bf16 v[118:121], v[174:177], v[190:193], v[118:121]
	v_mfma_f32_16x16x32_bf16 v[114:117], v[178:181], v[186:189], v[114:117]
	v_mfma_f32_16x16x32_bf16 v[114:117], v[182:185], v[190:193], v[114:117]
	v_mfma_f32_16x16x32_bf16 v[102:105], v[170:173], v[194:197], v[102:105]
	v_mfma_f32_16x16x32_bf16 v[102:105], v[174:177], v[198:201], v[102:105]
	v_mfma_f32_16x16x32_bf16 v[98:101], v[178:181], v[194:197], v[98:101]
	v_mfma_f32_16x16x32_bf16 v[98:101], v[182:185], v[198:201], v[98:101]
	v_mfma_f32_16x16x32_bf16 v[86:89], v[170:173], v[202:205], v[86:89]
	v_mfma_f32_16x16x32_bf16 v[86:89], v[174:177], v[206:209], v[86:89]
	v_mfma_f32_16x16x32_bf16 v[82:85], v[178:181], v[202:205], v[82:85]
	v_mfma_f32_16x16x32_bf16 v[82:85], v[182:185], v[206:209], v[82:85]
	v_mfma_f32_16x16x32_bf16 v[70:73], v[170:173], v[210:213], v[70:73]
	v_mfma_f32_16x16x32_bf16 v[70:73], v[174:177], v[214:217], v[70:73]
	v_mfma_f32_16x16x32_bf16 v[66:69], v[178:181], v[210:213], v[66:69]
	v_mfma_f32_16x16x32_bf16 v[66:69], v[182:185], v[214:217], v[66:69]
	s_barrier
	s_add_i32 s44, s36, s27
	s_mov_b32 m0, s44
	ds_read_b128 v[186:189], v156 offset:16384
	ds_read_b128 v[190:193], v156 offset:17408
	ds_read_b128 v[194:197], v156 offset:18432
	ds_read_b128 v[198:201], v156 offset:19456
	ds_read_b128 v[202:205], v156 offset:20480
	ds_read_b128 v[206:209], v156 offset:21504
	ds_read_b128 v[210:213], v156 offset:22528
	ds_read_b128 v[214:217], v156 offset:23552
	global_load_lds_dwordx4 v132, s[22:23]
	s_add_i32 m0, s44, 0x2000
	s_add_u32 s44, s22, 0x80000
	s_addc_u32 s45, s23, 0
	s_add_i32 s46, s37, s27
	global_load_lds_dwordx4 v136, s[22:23]
	s_mov_b32 m0, s46
	global_load_lds_dwordx4 v132, s[44:45]
	s_add_i32 m0, s46, 0x2000
	s_nop 0
	global_load_lds_dwordx4 v136, s[44:45]
	s_mov_b32 m0, s19
	s_nop 0
	global_load_lds_dwordx4 v130, s[24:25]
	s_mov_b32 m0, s28
	s_nop 0
	global_load_lds_dwordx4 v134, s[24:25]
	s_waitcnt vmcnt(8)
	s_cbranch_vccnz .Ldefl_863_1
	s_waitcnt lgkmcnt(0)
.Ldefl_863_1:
	s_barrier
	s_waitcnt lgkmcnt(0)
	v_mfma_f32_16x16x32_bf16 v[62:65], v[146:149], v[186:189], v[62:65]
	v_mfma_f32_16x16x32_bf16 v[62:65], v[158:161], v[190:193], v[62:65]
	v_mfma_f32_16x16x32_bf16 v[58:61], v[162:165], v[186:189], v[58:61]
	v_mfma_f32_16x16x32_bf16 v[58:61], v[166:169], v[190:193], v[58:61]
	v_mfma_f32_16x16x32_bf16 v[46:49], v[146:149], v[194:197], v[46:49]
	v_mfma_f32_16x16x32_bf16 v[46:49], v[158:161], v[198:201], v[46:49]
	v_mfma_f32_16x16x32_bf16 v[42:45], v[162:165], v[194:197], v[42:45]
	v_mfma_f32_16x16x32_bf16 v[42:45], v[166:169], v[198:201], v[42:45]
	v_mfma_f32_16x16x32_bf16 v[30:33], v[146:149], v[202:205], v[30:33]
	v_mfma_f32_16x16x32_bf16 v[30:33], v[158:161], v[206:209], v[30:33]
	v_mfma_f32_16x16x32_bf16 v[26:29], v[162:165], v[202:205], v[26:29]
	v_mfma_f32_16x16x32_bf16 v[26:29], v[166:169], v[206:209], v[26:29]
	v_mfma_f32_16x16x32_bf16 v[14:17], v[146:149], v[210:213], v[14:17]
	v_mfma_f32_16x16x32_bf16 v[14:17], v[158:161], v[214:217], v[14:17]
	v_mfma_f32_16x16x32_bf16 v[10:13], v[162:165], v[210:213], v[10:13]
	v_mfma_f32_16x16x32_bf16 v[10:13], v[166:169], v[214:217], v[10:13]
	v_mfma_f32_16x16x32_bf16 v[54:57], v[170:173], v[186:189], v[54:57]
	v_mfma_f32_16x16x32_bf16 v[54:57], v[174:177], v[190:193], v[54:57]
	v_mfma_f32_16x16x32_bf16 v[50:53], v[178:181], v[186:189], v[50:53]
	v_mfma_f32_16x16x32_bf16 v[50:53], v[182:185], v[190:193], v[50:53]
	v_mfma_f32_16x16x32_bf16 v[38:41], v[170:173], v[194:197], v[38:41]
	v_mfma_f32_16x16x32_bf16 v[38:41], v[174:177], v[198:201], v[38:41]
	v_mfma_f32_16x16x32_bf16 v[34:37], v[178:181], v[194:197], v[34:37]
	v_mfma_f32_16x16x32_bf16 v[34:37], v[182:185], v[198:201], v[34:37]
	v_mfma_f32_16x16x32_bf16 v[22:25], v[170:173], v[202:205], v[22:25]
	v_mfma_f32_16x16x32_bf16 v[22:25], v[174:177], v[206:209], v[22:25]
	v_mfma_f32_16x16x32_bf16 v[18:21], v[178:181], v[202:205], v[18:21]
	v_mfma_f32_16x16x32_bf16 v[18:21], v[182:185], v[206:209], v[18:21]
	v_mfma_f32_16x16x32_bf16 v[6:9], v[170:173], v[210:213], v[6:9]
	v_mfma_f32_16x16x32_bf16 v[6:9], v[174:177], v[214:217], v[6:9]
	v_mfma_f32_16x16x32_bf16 v[2:5], v[178:181], v[210:213], v[2:5]
	v_mfma_f32_16x16x32_bf16 v[2:5], v[182:185], v[214:217], v[2:5]
	s_barrier
	s_add_i32 s44, 0, 0x18000
	s_add_i32 s45, 0, 0x1c000
	ds_read_b128 v[146:149], v246
	ds_read_b128 v[158:161], v246 offset:1024
	ds_read_b128 v[162:165], v246 offset:2048
	ds_read_b128 v[166:169], v246 offset:3072
	ds_read_b128 v[170:173], v247
	ds_read_b128 v[174:177], v247 offset:1024
	ds_read_b128 v[178:181], v247 offset:2048
	ds_read_b128 v[182:185], v247 offset:3072
	s_add_u32 s98, s24, 0x80
	s_addc_u32 s99, s25, 0
	s_add_u32 s24, s24, 0x80000
	s_addc_u32 s25, s25, 0
	s_mov_b32 m0, s29
	ds_read_b128 v[186:189], v156 offset:32768
	ds_read_b128 v[190:193], v156 offset:33792
	ds_read_b128 v[194:197], v156 offset:34816
	ds_read_b128 v[198:201], v156 offset:35840
	ds_read_b128 v[202:205], v156 offset:36864
	ds_read_b128 v[206:209], v156 offset:37888
	ds_read_b128 v[210:213], v156 offset:38912
	ds_read_b128 v[214:217], v156 offset:39936
	global_load_lds_dwordx4 v130, s[24:25]
	s_mov_b32 m0, s30
	s_nop 0
	global_load_lds_dwordx4 v134, s[24:25]
	s_waitcnt vmcnt(8)
	s_cbranch_vccnz .Ldefl_863_2
	s_waitcnt lgkmcnt(0)
.Ldefl_863_2:
	s_barrier
	s_waitcnt lgkmcnt(0)
	v_mfma_f32_16x16x32_bf16 v[126:129], v[146:149], v[186:189], v[126:129]
	v_mfma_f32_16x16x32_bf16 v[126:129], v[158:161], v[190:193], v[126:129]
	v_mfma_f32_16x16x32_bf16 v[122:125], v[162:165], v[186:189], v[122:125]
	v_mfma_f32_16x16x32_bf16 v[122:125], v[166:169], v[190:193], v[122:125]
	v_mfma_f32_16x16x32_bf16 v[110:113], v[146:149], v[194:197], v[110:113]
	v_mfma_f32_16x16x32_bf16 v[110:113], v[158:161], v[198:201], v[110:113]
	v_mfma_f32_16x16x32_bf16 v[106:109], v[162:165], v[194:197], v[106:109]
	v_mfma_f32_16x16x32_bf16 v[106:109], v[166:169], v[198:201], v[106:109]
	v_mfma_f32_16x16x32_bf16 v[94:97], v[146:149], v[202:205], v[94:97]
	v_mfma_f32_16x16x32_bf16 v[94:97], v[158:161], v[206:209], v[94:97]
	v_mfma_f32_16x16x32_bf16 v[90:93], v[162:165], v[202:205], v[90:93]
	v_mfma_f32_16x16x32_bf16 v[90:93], v[166:169], v[206:209], v[90:93]
	v_mfma_f32_16x16x32_bf16 v[78:81], v[146:149], v[210:213], v[78:81]
	v_mfma_f32_16x16x32_bf16 v[78:81], v[158:161], v[214:217], v[78:81]
	v_mfma_f32_16x16x32_bf16 v[74:77], v[162:165], v[210:213], v[74:77]
	v_mfma_f32_16x16x32_bf16 v[74:77], v[166:169], v[214:217], v[74:77]
	v_mfma_f32_16x16x32_bf16 v[118:121], v[170:173], v[186:189], v[118:121]
	v_mfma_f32_16x16x32_bf16 v[118:121], v[174:177], v[190:193], v[118:121]
	v_mfma_f32_16x16x32_bf16 v[114:117], v[178:181], v[186:189], v[114:117]
	v_mfma_f32_16x16x32_bf16 v[114:117], v[182:185], v[190:193], v[114:117]
	v_mfma_f32_16x16x32_bf16 v[102:105], v[170:173], v[194:197], v[102:105]
	v_mfma_f32_16x16x32_bf16 v[102:105], v[174:177], v[198:201], v[102:105]
	v_mfma_f32_16x16x32_bf16 v[98:101], v[178:181], v[194:197], v[98:101]
	v_mfma_f32_16x16x32_bf16 v[98:101], v[182:185], v[198:201], v[98:101]
	v_mfma_f32_16x16x32_bf16 v[86:89], v[170:173], v[202:205], v[86:89]
	v_mfma_f32_16x16x32_bf16 v[86:89], v[174:177], v[206:209], v[86:89]
	v_mfma_f32_16x16x32_bf16 v[82:85], v[178:181], v[202:205], v[82:85]
	v_mfma_f32_16x16x32_bf16 v[82:85], v[182:185], v[206:209], v[82:85]
	v_mfma_f32_16x16x32_bf16 v[70:73], v[170:173], v[210:213], v[70:73]
	v_mfma_f32_16x16x32_bf16 v[70:73], v[174:177], v[214:217], v[70:73]
	v_mfma_f32_16x16x32_bf16 v[66:69], v[178:181], v[210:213], v[66:69]
	v_mfma_f32_16x16x32_bf16 v[66:69], v[182:185], v[214:217], v[66:69]
	s_barrier
	s_add_i32 s24, s44, s27
	s_mov_b32 m0, s24
	ds_read_b128 v[186:189], v156 offset:49152
	ds_read_b128 v[190:193], v156 offset:50176
	ds_read_b128 v[194:197], v156 offset:51200
	ds_read_b128 v[198:201], v156 offset:52224
	ds_read_b128 v[202:205], v156 offset:53248
	ds_read_b128 v[206:209], v156 offset:54272
	ds_read_b128 v[210:213], v156 offset:55296
	ds_read_b128 v[214:217], v156 offset:56320
	s_add_u32 s22, s22, 0x80
	s_addc_u32 s23, s23, 0
	global_load_lds_dwordx4 v132, s[22:23]
	s_add_i32 m0, s24, 0x2000
	s_add_i32 s24, s45, s27
	global_load_lds_dwordx4 v136, s[22:23]
	s_add_u32 s22, s22, 0x80000
	s_addc_u32 s23, s23, 0
	s_mov_b32 m0, s24
	s_nop 0
	global_load_lds_dwordx4 v132, s[22:23]
	s_add_i32 m0, s24, 0x2000
	s_nop 0
	global_load_lds_dwordx4 v136, s[22:23]
	s_mov_b32 m0, s33
	s_nop 0
	global_load_lds_dwordx4 v130, s[98:99]
	s_mov_b32 m0, s34
	s_nop 0
	global_load_lds_dwordx4 v134, s[98:99]
	s_waitcnt vmcnt(8)
	s_cbranch_vccnz .Ldefl_863_3
	s_waitcnt lgkmcnt(0)
.Ldefl_863_3:
	s_barrier
	s_waitcnt lgkmcnt(0)
	v_mfma_f32_16x16x32_bf16 v[62:65], v[146:149], v[186:189], v[62:65]
	v_mfma_f32_16x16x32_bf16 v[62:65], v[158:161], v[190:193], v[62:65]
	v_mfma_f32_16x16x32_bf16 v[58:61], v[162:165], v[186:189], v[58:61]
	v_mfma_f32_16x16x32_bf16 v[58:61], v[166:169], v[190:193], v[58:61]
	v_mfma_f32_16x16x32_bf16 v[46:49], v[146:149], v[194:197], v[46:49]
	v_mfma_f32_16x16x32_bf16 v[46:49], v[158:161], v[198:201], v[46:49]
	v_mfma_f32_16x16x32_bf16 v[42:45], v[162:165], v[194:197], v[42:45]
	v_mfma_f32_16x16x32_bf16 v[42:45], v[166:169], v[198:201], v[42:45]
	v_mfma_f32_16x16x32_bf16 v[30:33], v[146:149], v[202:205], v[30:33]
	v_mfma_f32_16x16x32_bf16 v[30:33], v[158:161], v[206:209], v[30:33]
	v_mfma_f32_16x16x32_bf16 v[26:29], v[162:165], v[202:205], v[26:29]
	v_mfma_f32_16x16x32_bf16 v[26:29], v[166:169], v[206:209], v[26:29]
	v_mfma_f32_16x16x32_bf16 v[14:17], v[146:149], v[210:213], v[14:17]
	v_mfma_f32_16x16x32_bf16 v[14:17], v[158:161], v[214:217], v[14:17]
	v_mfma_f32_16x16x32_bf16 v[10:13], v[162:165], v[210:213], v[10:13]
	v_mfma_f32_16x16x32_bf16 v[10:13], v[166:169], v[214:217], v[10:13]
	v_mfma_f32_16x16x32_bf16 v[54:57], v[170:173], v[186:189], v[54:57]
	v_mfma_f32_16x16x32_bf16 v[54:57], v[174:177], v[190:193], v[54:57]
	v_mfma_f32_16x16x32_bf16 v[50:53], v[178:181], v[186:189], v[50:53]
	v_mfma_f32_16x16x32_bf16 v[50:53], v[182:185], v[190:193], v[50:53]
	v_mfma_f32_16x16x32_bf16 v[38:41], v[170:173], v[194:197], v[38:41]
	v_mfma_f32_16x16x32_bf16 v[38:41], v[174:177], v[198:201], v[38:41]
	v_mfma_f32_16x16x32_bf16 v[34:37], v[178:181], v[194:197], v[34:37]
	v_mfma_f32_16x16x32_bf16 v[34:37], v[182:185], v[198:201], v[34:37]
	v_mfma_f32_16x16x32_bf16 v[22:25], v[170:173], v[202:205], v[22:25]
	v_mfma_f32_16x16x32_bf16 v[22:25], v[174:177], v[206:209], v[22:25]
	v_mfma_f32_16x16x32_bf16 v[18:21], v[178:181], v[202:205], v[18:21]
	v_mfma_f32_16x16x32_bf16 v[18:21], v[182:185], v[206:209], v[18:21]
	v_mfma_f32_16x16x32_bf16 v[6:9], v[170:173], v[210:213], v[6:9]
	v_mfma_f32_16x16x32_bf16 v[6:9], v[174:177], v[214:217], v[6:9]
	v_mfma_f32_16x16x32_bf16 v[2:5], v[178:181], v[210:213], v[2:5]
	v_mfma_f32_16x16x32_bf16 v[2:5], v[182:185], v[214:217], v[2:5]
	s_barrier
	s_add_i32 s43, s43, 2
	s_add_u32 s20, s20, 0x100
	s_addc_u32 s21, s21, 0
	s_add_u32 s41, s41, 0x100
	s_addc_u32 s42, s42, 0
	s_cmp_gt_u32 s43, 29
	s_cbranch_scc0 .LBB0_863
	s_and_b64 vcc, exec, s[8:9]
	s_cbranch_vccz .LBB0_866
	s_barrier

.LBB0_940:
	s_ashr_i32 s21, s20, 31
	s_lshl_b64 s[22:23], s[20:21], 21
	s_add_u32 s22, s0, s22
	s_addc_u32 s23, s1, s23
	s_and_b64 s[24:25], s[4:5], exec
	s_cselect_b32 s21, s23, s29
	s_cselect_b32 s27, s22, s28
	s_ashr_i32 s19, s18, 31
	s_lshl_b64 s[24:25], s[18:19], 21
	v_readlane_b32 s34, v245, 18
	v_readlane_b32 s35, v245, 19
	s_add_u32 s24, s34, s24
	s_addc_u32 s25, s35, s25
	s_and_b64 s[34:35], s[4:5], exec
	s_cselect_b32 s19, s25, s31
	s_cselect_b32 s48, s24, s30
	s_add_u32 s28, s28, 0x100080
	s_addc_u32 s29, s29, 0
	s_add_u32 s49, s30, 0x100
	v_mov_b32_e32 v2, 0
	s_addc_u32 s50, s31, 0
	s_mov_b32 s51, -2
	s_waitcnt lgkmcnt(0)
	v_mov_b64_e32 v[2:3], 0
	v_mov_b64_e32 v[4:5], 0
	v_mov_b64_e32 v[6:7], 0
	v_mov_b64_e32 v[8:9], 0
	v_mov_b64_e32 v[10:11], 0
	v_mov_b64_e32 v[12:13], 0
	v_mov_b64_e32 v[14:15], 0
	v_mov_b64_e32 v[16:17], 0
	v_mov_b64_e32 v[18:19], 0
	v_mov_b64_e32 v[20:21], 0
	v_mov_b64_e32 v[22:23], 0
	v_mov_b64_e32 v[24:25], 0
	v_mov_b64_e32 v[26:27], 0
	v_mov_b64_e32 v[28:29], 0
	v_mov_b64_e32 v[30:31], 0
	v_mov_b64_e32 v[32:33], 0
	v_mov_b64_e32 v[34:35], 0
	v_mov_b64_e32 v[36:37], 0
	v_mov_b64_e32 v[38:39], 0
	v_mov_b64_e32 v[40:41], 0
	v_mov_b64_e32 v[42:43], 0
	v_mov_b64_e32 v[44:45], 0
	v_mov_b64_e32 v[46:47], 0
	v_mov_b64_e32 v[48:49], 0
	v_mov_b64_e32 v[50:51], 0
	v_mov_b64_e32 v[52:53], 0
	v_mov_b64_e32 v[54:55], 0
	v_mov_b64_e32 v[56:57], 0
	v_mov_b64_e32 v[58:59], 0
	v_mov_b64_e32 v[60:61], 0
	v_mov_b64_e32 v[62:63], 0
	v_mov_b64_e32 v[64:65], 0
	v_mov_b64_e32 v[66:67], 0
	v_mov_b64_e32 v[68:69], 0
	v_mov_b64_e32 v[70:71], 0
	v_mov_b64_e32 v[72:73], 0
	v_mov_b64_e32 v[82:83], 0
	v_mov_b64_e32 v[84:85], 0
	v_mov_b64_e32 v[86:87], 0
	v_mov_b64_e32 v[88:89], 0
	s_waitcnt vmcnt(0)
	v_mov_b64_e32 v[74:75], 0
	v_mov_b64_e32 v[76:77], 0
	v_mov_b64_e32 v[78:79], 0
	v_mov_b64_e32 v[80:81], 0
	v_mov_b64_e32 v[98:99], 0
	v_mov_b64_e32 v[100:101], 0
	v_mov_b64_e32 v[106:107], 0
	v_mov_b64_e32 v[108:109], 0
	v_mov_b64_e32 v[114:115], 0
	v_mov_b64_e32 v[116:117], 0
	v_mov_b64_e32 v[118:119], 0
	v_mov_b64_e32 v[120:121], 0
	v_mov_b64_e32 v[122:123], 0
	v_mov_b64_e32 v[124:125], 0
	v_mov_b64_e32 v[126:127], 0
	v_mov_b64_e32 v[128:129], 0
	v_mov_b64_e32 v[130:131], 0
	v_mov_b64_e32 v[132:133], 0
	v_mov_b64_e32 v[134:135], 0
	v_mov_b64_e32 v[136:137], 0
	v_mov_b64_e32 v[138:139], 0
	v_mov_b64_e32 v[140:141], 0
	v_mov_b64_e32 v[142:143], 0
	v_mov_b64_e32 v[144:145], 0
	v_add_u32_e32 v246, 0x18000, v186
	v_add_u32_e32 v247, 0x1c000, v186
	v_cmp_gt_u32_e32 vcc, 0x100, v0
.LBB0_941:
	ds_read_b128 v[90:93], v188
	ds_read_b128 v[94:97], v188 offset:1024
	ds_read_b128 v[102:105], v188 offset:2048
	ds_read_b128 v[110:113], v188 offset:3072
	ds_read_b128 v[146:149], v189
	ds_read_b128 v[150:153], v189 offset:1024
	ds_read_b128 v[154:157], v189 offset:2048
	ds_read_b128 v[158:161], v189 offset:3072
	s_add_u32 s30, s28, 0xfff00080
	s_addc_u32 s31, s29, -1
	s_cmp_eq_u32 s51, 60
	s_cselect_b32 s35, s21, s31
	s_cselect_b32 s34, s27, s30
	s_cselect_b32 s31, s19, s50
	s_cselect_b32 s30, s48, s49
	s_add_i32 m0, s36, 0xc000
	ds_read_b128 v[178:181], v190
	ds_read_b128 v[182:185], v190 offset:1024
	ds_read_b128 v[192:195], v190 offset:2048
	ds_read_b128 v[196:199], v190 offset:3072
	ds_read_b128 v[200:203], v190 offset:4096
	ds_read_b128 v[204:207], v190 offset:5120
	ds_read_b128 v[208:211], v190 offset:6144
	ds_read_b128 v[212:215], v190 offset:7168
	global_load_lds_dwordx4 v170, s[28:29]
	s_add_i32 m0, s36, 0xe000
	s_nop 0
	global_load_lds_dwordx4 v172, s[28:29]
	s_waitcnt vmcnt(8)
	s_cbranch_vccnz .Ldefl_941_0
	s_waitcnt lgkmcnt(0)
.Ldefl_941_0:
	s_barrier
	s_waitcnt lgkmcnt(0)
	v_mfma_f32_16x16x32_bf16 v[142:145], v[90:93], v[178:181], v[142:145]
	v_mfma_f32_16x16x32_bf16 v[142:145], v[94:97], v[182:185], v[142:145]
	v_mfma_f32_16x16x32_bf16 v[138:141], v[102:105], v[178:181], v[138:141]
	v_mfma_f32_16x16x32_bf16 v[138:141], v[110:113], v[182:185], v[138:141]
	v_mfma_f32_16x16x32_bf16 v[126:129], v[90:93], v[192:195], v[126:129]
	v_mfma_f32_16x16x32_bf16 v[126:129], v[94:97], v[196:199], v[126:129]
	v_mfma_f32_16x16x32_bf16 v[122:125], v[102:105], v[192:195], v[122:125]
	v_mfma_f32_16x16x32_bf16 v[122:125], v[110:113], v[196:199], v[122:125]
	v_mfma_f32_16x16x32_bf16 v[106:109], v[90:93], v[200:203], v[106:109]
	v_mfma_f32_16x16x32_bf16 v[106:109], v[94:97], v[204:207], v[106:109]
	v_mfma_f32_16x16x32_bf16 v[98:101], v[102:105], v[200:203], v[98:101]
	v_mfma_f32_16x16x32_bf16 v[98:101], v[110:113], v[204:207], v[98:101]
	v_mfma_f32_16x16x32_bf16 v[78:81], v[90:93], v[208:211], v[78:81]
	v_mfma_f32_16x16x32_bf16 v[78:81], v[94:97], v[212:215], v[78:81]
	v_mfma_f32_16x16x32_bf16 v[74:77], v[102:105], v[208:211], v[74:77]
	v_mfma_f32_16x16x32_bf16 v[74:77], v[110:113], v[212:215], v[74:77]
	v_mfma_f32_16x16x32_bf16 v[134:137], v[146:149], v[178:181], v[134:137]
	v_mfma_f32_16x16x32_bf16 v[134:137], v[150:153], v[182:185], v[134:137]
	v_mfma_f32_16x16x32_bf16 v[130:133], v[154:157], v[178:181], v[130:133]
	v_mfma_f32_16x16x32_bf16 v[130:133], v[158:161], v[182:185], v[130:133]
	v_mfma_f32_16x16x32_bf16 v[118:121], v[146:149], v[192:195], v[118:121]
	v_mfma_f32_16x16x32_bf16 v[118:121], v[150:153], v[196:199], v[118:121]
	v_mfma_f32_16x16x32_bf16 v[114:117], v[154:157], v[192:195], v[114:117]
	v_mfma_f32_16x16x32_bf16 v[114:117], v[158:161], v[196:199], v[114:117]
	v_mfma_f32_16x16x32_bf16 v[86:89], v[146:149], v[200:203], v[86:89]
	v_mfma_f32_16x16x32_bf16 v[86:89], v[150:153], v[204:207], v[86:89]
	v_mfma_f32_16x16x32_bf16 v[82:85], v[154:157], v[200:203], v[82:85]
	v_mfma_f32_16x16x32_bf16 v[82:85], v[158:161], v[204:207], v[82:85]
	v_mfma_f32_16x16x32_bf16 v[70:73], v[146:149], v[208:211], v[70:73]
	v_mfma_f32_16x16x32_bf16 v[70:73], v[150:153], v[212:215], v[70:73]
	v_mfma_f32_16x16x32_bf16 v[66:69], v[154:157], v[208:211], v[66:69]
	v_mfma_f32_16x16x32_bf16 v[66:69], v[158:161], v[212:215], v[66:69]
	s_barrier
	s_add_i32 s52, s45, s33
	s_mov_b32 m0, s52
	ds_read_b128 v[178:181], v190 offset:16384
	ds_read_b128 v[182:185], v190 offset:17408
	ds_read_b128 v[192:195], v190 offset:18432
	ds_read_b128 v[196:199], v190 offset:19456
	ds_read_b128 v[200:203], v190 offset:20480
	ds_read_b128 v[204:207], v190 offset:21504
	ds_read_b128 v[208:211], v190 offset:22528
	ds_read_b128 v[212:215], v190 offset:23552
	global_load_lds_dwordx4 v164, s[30:31]
	s_add_i32 m0, s52, 0x2000
	s_add_u32 s52, s30, 0x100000
	s_addc_u32 s53, s31, 0
	s_add_i32 s54, s46, s33
	global_load_lds_dwordx4 v168, s[30:31]
	s_mov_b32 m0, s54
	global_load_lds_dwordx4 v164, s[52:53]
	s_add_i32 m0, s54, 0x2000
	s_nop 0
	global_load_lds_dwordx4 v168, s[52:53]
	s_mov_b32 m0, s36
	s_nop 0
	global_load_lds_dwordx4 v162, s[34:35]
	s_mov_b32 m0, s37
	s_nop 0
	global_load_lds_dwordx4 v166, s[34:35]
	s_waitcnt vmcnt(8)
	s_cbranch_vccnz .Ldefl_941_1
	s_waitcnt lgkmcnt(0)
.Ldefl_941_1:
	s_barrier
	s_waitcnt lgkmcnt(0)
	v_mfma_f32_16x16x32_bf16 v[62:65], v[90:93], v[178:181], v[62:65]
	v_mfma_f32_16x16x32_bf16 v[62:65], v[94:97], v[182:185], v[62:65]
	v_mfma_f32_16x16x32_bf16 v[58:61], v[102:105], v[178:181], v[58:61]
	v_mfma_f32_16x16x32_bf16 v[58:61], v[110:113], v[182:185], v[58:61]
	v_mfma_f32_16x16x32_bf16 v[46:49], v[90:93], v[192:195], v[46:49]
	v_mfma_f32_16x16x32_bf16 v[46:49], v[94:97], v[196:199], v[46:49]
	v_mfma_f32_16x16x32_bf16 v[42:45], v[102:105], v[192:195], v[42:45]
	v_mfma_f32_16x16x32_bf16 v[42:45], v[110:113], v[196:199], v[42:45]
	v_mfma_f32_16x16x32_bf16 v[30:33], v[90:93], v[200:203], v[30:33]
	v_mfma_f32_16x16x32_bf16 v[30:33], v[94:97], v[204:207], v[30:33]
	v_mfma_f32_16x16x32_bf16 v[26:29], v[102:105], v[200:203], v[26:29]
	v_mfma_f32_16x16x32_bf16 v[26:29], v[110:113], v[204:207], v[26:29]
	v_mfma_f32_16x16x32_bf16 v[14:17], v[90:93], v[208:211], v[14:17]
	v_mfma_f32_16x16x32_bf16 v[14:17], v[94:97], v[212:215], v[14:17]
	v_mfma_f32_16x16x32_bf16 v[10:13], v[102:105], v[208:211], v[10:13]
	v_mfma_f32_16x16x32_bf16 v[10:13], v[110:113], v[212:215], v[10:13]
	v_mfma_f32_16x16x32_bf16 v[54:57], v[146:149], v[178:181], v[54:57]
	v_mfma_f32_16x16x32_bf16 v[54:57], v[150:153], v[182:185], v[54:57]
	v_mfma_f32_16x16x32_bf16 v[50:53], v[154:157], v[178:181], v[50:53]
	v_mfma_f32_16x16x32_bf16 v[50:53], v[158:161], v[182:185], v[50:53]
	v_mfma_f32_16x16x32_bf16 v[38:41], v[146:149], v[192:195], v[38:41]
	v_mfma_f32_16x16x32_bf16 v[38:41], v[150:153], v[196:199], v[38:41]
	v_mfma_f32_16x16x32_bf16 v[34:37], v[154:157], v[192:195], v[34:37]
	v_mfma_f32_16x16x32_bf16 v[34:37], v[158:161], v[196:199], v[34:37]
	v_mfma_f32_16x16x32_bf16 v[22:25], v[146:149], v[200:203], v[22:25]
	v_mfma_f32_16x16x32_bf16 v[22:25], v[150:153], v[204:207], v[22:25]
	v_mfma_f32_16x16x32_bf16 v[18:21], v[154:157], v[200:203], v[18:21]
	v_mfma_f32_16x16x32_bf16 v[18:21], v[158:161], v[204:207], v[18:21]
	v_mfma_f32_16x16x32_bf16 v[6:9], v[146:149], v[208:211], v[6:9]
	v_mfma_f32_16x16x32_bf16 v[6:9], v[150:153], v[212:215], v[6:9]
	v_mfma_f32_16x16x32_bf16 v[2:5], v[154:157], v[208:211], v[2:5]
	v_mfma_f32_16x16x32_bf16 v[2:5], v[158:161], v[212:215], v[2:5]
	s_barrier
	s_add_i32 s52, 0, 0x18000
	s_add_i32 s53, 0, 0x1c000
	ds_read_b128 v[90:93], v246
	ds_read_b128 v[94:97], v246 offset:1024
	ds_read_b128 v[102:105], v246 offset:2048
	ds_read_b128 v[110:113], v246 offset:3072
	ds_read_b128 v[146:149], v247
	ds_read_b128 v[150:153], v247 offset:1024
	ds_read_b128 v[154:157], v247 offset:2048
	ds_read_b128 v[158:161], v247 offset:3072
	s_add_u32 s98, s34, 0x80
	s_addc_u32 s99, s35, 0
	s_add_u32 s34, s34, 0x100000
	s_addc_u32 s35, s35, 0
	s_mov_b32 m0, s38
	ds_read_b128 v[178:181], v190 offset:32768
	ds_read_b128 v[182:185], v190 offset:33792
	ds_read_b128 v[192:195], v190 offset:34816
	ds_read_b128 v[196:199], v190 offset:35840
	ds_read_b128 v[200:203], v190 offset:36864
	ds_read_b128 v[204:207], v190 offset:37888
	ds_read_b128 v[208:211], v190 offset:38912
	ds_read_b128 v[212:215], v190 offset:39936
	global_load_lds_dwordx4 v162, s[34:35]
	s_mov_b32 m0, s39
	s_nop 0
	global_load_lds_dwordx4 v166, s[34:35]
	s_waitcnt vmcnt(8)
	s_cbranch_vccnz .Ldefl_941_2
	s_waitcnt lgkmcnt(0)
.Ldefl_941_2:
	s_barrier
	s_waitcnt lgkmcnt(0)
	v_mfma_f32_16x16x32_bf16 v[142:145], v[90:93], v[178:181], v[142:145]
	v_mfma_f32_16x16x32_bf16 v[142:145], v[94:97], v[182:185], v[142:145]
	v_mfma_f32_16x16x32_bf16 v[138:141], v[102:105], v[178:181], v[138:141]
	v_mfma_f32_16x16x32_bf16 v[138:141], v[110:113], v[182:185], v[138:141]
	v_mfma_f32_16x16x32_bf16 v[126:129], v[90:93], v[192:195], v[126:129]
	v_mfma_f32_16x16x32_bf16 v[126:129], v[94:97], v[196:199], v[126:129]
	v_mfma_f32_16x16x32_bf16 v[122:125], v[102:105], v[192:195], v[122:125]
	v_mfma_f32_16x16x32_bf16 v[122:125], v[110:113], v[196:199], v[122:125]
	v_mfma_f32_16x16x32_bf16 v[106:109], v[90:93], v[200:203], v[106:109]
	v_mfma_f32_16x16x32_bf16 v[106:109], v[94:97], v[204:207], v[106:109]
	v_mfma_f32_16x16x32_bf16 v[98:101], v[102:105], v[200:203], v[98:101]
	v_mfma_f32_16x16x32_bf16 v[98:101], v[110:113], v[204:207], v[98:101]
	v_mfma_f32_16x16x32_bf16 v[78:81], v[90:93], v[208:211], v[78:81]
	v_mfma_f32_16x16x32_bf16 v[78:81], v[94:97], v[212:215], v[78:81]
	v_mfma_f32_16x16x32_bf16 v[74:77], v[102:105], v[208:211], v[74:77]
	v_mfma_f32_16x16x32_bf16 v[74:77], v[110:113], v[212:215], v[74:77]
	v_mfma_f32_16x16x32_bf16 v[134:137], v[146:149], v[178:181], v[134:137]
	v_mfma_f32_16x16x32_bf16 v[134:137], v[150:153], v[182:185], v[134:137]
	v_mfma_f32_16x16x32_bf16 v[130:133], v[154:157], v[178:181], v[130:133]
	v_mfma_f32_16x16x32_bf16 v[130:133], v[158:161], v[182:185], v[130:133]
	v_mfma_f32_16x16x32_bf16 v[118:121], v[146:149], v[192:195], v[118:121]
	v_mfma_f32_16x16x32_bf16 v[118:121], v[150:153], v[196:199], v[118:121]
	v_mfma_f32_16x16x32_bf16 v[114:117], v[154:157], v[192:195], v[114:117]
	v_mfma_f32_16x16x32_bf16 v[114:117], v[158:161], v[196:199], v[114:117]
	v_mfma_f32_16x16x32_bf16 v[86:89], v[146:149], v[200:203], v[86:89]
	v_mfma_f32_16x16x32_bf16 v[86:89], v[150:153], v[204:207], v[86:89]
	v_mfma_f32_16x16x32_bf16 v[82:85], v[154:157], v[200:203], v[82:85]
	v_mfma_f32_16x16x32_bf16 v[82:85], v[158:161], v[204:207], v[82:85]
	v_mfma_f32_16x16x32_bf16 v[70:73], v[146:149], v[208:211], v[70:73]
	v_mfma_f32_16x16x32_bf16 v[70:73], v[150:153], v[212:215], v[70:73]
	v_mfma_f32_16x16x32_bf16 v[66:69], v[154:157], v[208:211], v[66:69]
	v_mfma_f32_16x16x32_bf16 v[66:69], v[158:161], v[212:215], v[66:69]
	s_barrier
	s_add_i32 s34, s52, s33
	s_mov_b32 m0, s34
	ds_read_b128 v[178:181], v190 offset:49152
	ds_read_b128 v[182:185], v190 offset:50176
	ds_read_b128 v[192:195], v190 offset:51200
	ds_read_b128 v[196:199], v190 offset:52224
	ds_read_b128 v[200:203], v190 offset:53248
	ds_read_b128 v[204:207], v190 offset:54272
	ds_read_b128 v[208:211], v190 offset:55296
	ds_read_b128 v[212:215], v190 offset:56320
	s_add_u32 s30, s30, 0x80
	s_addc_u32 s31, s31, 0
	global_load_lds_dwordx4 v164, s[30:31]
	s_add_i32 m0, s34, 0x2000
	s_add_i32 s34, s53, s33
	global_load_lds_dwordx4 v168, s[30:31]
	s_add_u32 s30, s30, 0x100000
	s_addc_u32 s31, s31, 0
	s_mov_b32 m0, s34
	s_nop 0
	global_load_lds_dwordx4 v164, s[30:31]
	s_add_i32 m0, s34, 0x2000
	s_nop 0
	global_load_lds_dwordx4 v168, s[30:31]
	s_mov_b32 m0, s43
	s_nop 0
	global_load_lds_dwordx4 v162, s[98:99]
	s_mov_b32 m0, s44
	s_nop 0
	global_load_lds_dwordx4 v166, s[98:99]
	s_waitcnt vmcnt(8)
	s_cbranch_vccnz .Ldefl_941_3
	s_waitcnt lgkmcnt(0)
.Ldefl_941_3:
	s_barrier
	s_waitcnt lgkmcnt(0)
	v_mfma_f32_16x16x32_bf16 v[62:65], v[90:93], v[178:181], v[62:65]
	v_mfma_f32_16x16x32_bf16 v[62:65], v[94:97], v[182:185], v[62:65]
	v_mfma_f32_16x16x32_bf16 v[58:61], v[102:105], v[178:181], v[58:61]
	v_mfma_f32_16x16x32_bf16 v[58:61], v[110:113], v[182:185], v[58:61]
	v_mfma_f32_16x16x32_bf16 v[46:49], v[90:93], v[192:195], v[46:49]
	v_mfma_f32_16x16x32_bf16 v[46:49], v[94:97], v[196:199], v[46:49]
	v_mfma_f32_16x16x32_bf16 v[42:45], v[102:105], v[192:195], v[42:45]
	v_mfma_f32_16x16x32_bf16 v[42:45], v[110:113], v[196:199], v[42:45]
	v_mfma_f32_16x16x32_bf16 v[30:33], v[90:93], v[200:203], v[30:33]
	v_mfma_f32_16x16x32_bf16 v[30:33], v[94:97], v[204:207], v[30:33]
	v_mfma_f32_16x16x32_bf16 v[26:29], v[102:105], v[200:203], v[26:29]
	v_mfma_f32_16x16x32_bf16 v[26:29], v[110:113], v[204:207], v[26:29]
	v_mfma_f32_16x16x32_bf16 v[14:17], v[90:93], v[208:211], v[14:17]
	v_mfma_f32_16x16x32_bf16 v[14:17], v[94:97], v[212:215], v[14:17]
	v_mfma_f32_16x16x32_bf16 v[10:13], v[102:105], v[208:211], v[10:13]
	v_mfma_f32_16x16x32_bf16 v[10:13], v[110:113], v[212:215], v[10:13]
	v_mfma_f32_16x16x32_bf16 v[54:57], v[146:149], v[178:181], v[54:57]
	v_mfma_f32_16x16x32_bf16 v[54:57], v[150:153], v[182:185], v[54:57]
	v_mfma_f32_16x16x32_bf16 v[50:53], v[154:157], v[178:181], v[50:53]
	v_mfma_f32_16x16x32_bf16 v[50:53], v[158:161], v[182:185], v[50:53]
	v_mfma_f32_16x16x32_bf16 v[38:41], v[146:149], v[192:195], v[38:41]
	v_mfma_f32_16x16x32_bf16 v[38:41], v[150:153], v[196:199], v[38:41]
	v_mfma_f32_16x16x32_bf16 v[34:37], v[154:157], v[192:195], v[34:37]
	v_mfma_f32_16x16x32_bf16 v[34:37], v[158:161], v[196:199], v[34:37]
	v_mfma_f32_16x16x32_bf16 v[22:25], v[146:149], v[200:203], v[22:25]
	v_mfma_f32_16x16x32_bf16 v[22:25], v[150:153], v[204:207], v[22:25]
	v_mfma_f32_16x16x32_bf16 v[18:21], v[154:157], v[200:203], v[18:21]
	v_mfma_f32_16x16x32_bf16 v[18:21], v[158:161], v[204:207], v[18:21]
	v_mfma_f32_16x16x32_bf16 v[6:9], v[146:149], v[208:211], v[6:9]
	v_mfma_f32_16x16x32_bf16 v[6:9], v[150:153], v[212:215], v[6:9]
	v_mfma_f32_16x16x32_bf16 v[2:5], v[154:157], v[208:211], v[2:5]
	v_mfma_f32_16x16x32_bf16 v[2:5], v[158:161], v[212:215], v[2:5]
	s_barrier
	s_add_i32 s51, s51, 2
	s_add_u32 s28, s28, 0x100
	s_addc_u32 s29, s29, 0
	s_add_u32 s49, s49, 0x100
	s_addc_u32 s50, s50, 0
	s_cmp_gt_u32 s51, 61
	s_cbranch_scc0 .LBB0_941
	s_and_b64 vcc, exec, s[16:17]
	s_cbranch_vccz .LBB0_944
	s_barrier

.LBB0_1152:
	s_xor_b64 s[48:49], s[54:55], -1
	s_add_u32 s33, s56, 0x100
	s_addc_u32 s72, s57, 0
	s_ashr_i32 s45, s44, 31
	s_lshl_b64 s[50:51], s[44:45], 21
	s_add_u32 s50, s70, s50
	s_addc_u32 s51, s71, s51
	s_and_b64 s[52:53], s[54:55], exec
	s_cselect_b32 s29, s51, s47
	s_cselect_b32 s45, s50, s46
	s_ashr_i32 s43, s42, 31
	s_lshl_b64 s[52:53], s[42:43], 21
	v_readlane_b32 s20, v244, 4
	v_readlane_b32 s21, v244, 5
	s_add_u32 s52, s20, s52
	s_addc_u32 s53, s21, s53
	s_and_b64 s[58:59], s[54:55], exec
	s_cselect_b32 s43, s53, s57
	s_cselect_b32 s73, s52, s56
	v_lshl_add_u64 v[130:131], s[46:47], 0, v[196:197]
	v_lshl_add_u64 v[132:133], s[46:47], 0, v[198:199]
	s_mov_b32 s83, -2
	v_add_u32_e32 v246, 0x18000, v187
	v_add_u32_e32 v247, 0x1c000, v187
	v_cmp_gt_u32_e32 vcc, 0x100, v0
.LBB0_1153:
	v_add_u32_e32 v146, s78, v187
	v_add_u32_e32 v162, s79, v187
	s_add_u32 s98, s46, s10
	s_addc_u32 s99, s47, s11
	s_add_u32 s98, s98, 0x100080
	s_addc_u32 s99, s99, 0
	s_add_u32 s56, s46, s10
	ds_read_b128 v[134:137], v146
	ds_read_b128 v[138:141], v146 offset:1024
	ds_read_b128 v[142:145], v146 offset:2048
	ds_read_b128 v[146:149], v146 offset:3072
	ds_read_b128 v[150:153], v162
	ds_read_b128 v[154:157], v162 offset:1024
	ds_read_b128 v[158:161], v162 offset:2048
	ds_read_b128 v[162:165], v162 offset:3072
	s_addc_u32 s57, s47, s11
	s_add_u32 s56, s56, 0x100
	s_addc_u32 s57, s57, 0
	s_add_u32 s84, s33, s10
	s_addc_u32 s85, s72, s11
	s_cmpk_eq_i32 s10, 0x1f00
	s_cselect_b32 s59, s29, s57
	s_cselect_b32 s58, s45, s56
	s_cselect_b32 s57, s43, s85
	s_cselect_b32 s56, s73, s84
	s_add_i32 m0, s64, 0xc000
	ds_read_b128 v[166:169], v230
	ds_read_b128 v[170:173], v230 offset:1024
	ds_read_b128 v[174:177], v230 offset:2048
	ds_read_b128 v[202:205], v230 offset:3072
	ds_read_b128 v[206:209], v230 offset:4096
	ds_read_b128 v[210:213], v230 offset:5120
	ds_read_b128 v[214:217], v230 offset:6144
	ds_read_b128 v[218:221], v230 offset:7168
	global_load_lds_dwordx4 v178, s[98:99]
	s_add_i32 m0, s64, 0xe000
	s_nop 0
	global_load_lds_dwordx4 v182, s[98:99]
	s_waitcnt vmcnt(8)
	s_cbranch_vccnz .Ldefl_1153_0
	s_waitcnt lgkmcnt(0)
.Ldefl_1153_0:
	s_barrier
	s_waitcnt lgkmcnt(0)
	v_mfma_f32_16x16x32_bf16 v[2:5], v[134:137], v[166:169], v[2:5]
	v_mfma_f32_16x16x32_bf16 v[2:5], v[138:141], v[170:173], v[2:5]
	v_mfma_f32_16x16x32_bf16 v[126:129], v[142:145], v[166:169], v[126:129]
	v_mfma_f32_16x16x32_bf16 v[126:129], v[146:149], v[170:173], v[126:129]
	v_mfma_f32_16x16x32_bf16 v[122:125], v[134:137], v[174:177], v[122:125]
	v_mfma_f32_16x16x32_bf16 v[122:125], v[138:141], v[202:205], v[122:125]
	v_mfma_f32_16x16x32_bf16 v[118:121], v[142:145], v[174:177], v[118:121]
	v_mfma_f32_16x16x32_bf16 v[118:121], v[146:149], v[202:205], v[118:121]
	v_mfma_f32_16x16x32_bf16 v[114:117], v[134:137], v[206:209], v[114:117]
	v_mfma_f32_16x16x32_bf16 v[114:117], v[138:141], v[210:213], v[114:117]
	v_mfma_f32_16x16x32_bf16 v[110:113], v[142:145], v[206:209], v[110:113]
	v_mfma_f32_16x16x32_bf16 v[110:113], v[146:149], v[210:213], v[110:113]
	v_mfma_f32_16x16x32_bf16 v[106:109], v[134:137], v[214:217], v[106:109]
	v_mfma_f32_16x16x32_bf16 v[106:109], v[138:141], v[218:221], v[106:109]
	v_mfma_f32_16x16x32_bf16 v[102:105], v[142:145], v[214:217], v[102:105]
	v_mfma_f32_16x16x32_bf16 v[102:105], v[146:149], v[218:221], v[102:105]
	v_mfma_f32_16x16x32_bf16 v[98:101], v[150:153], v[166:169], v[98:101]
	v_mfma_f32_16x16x32_bf16 v[98:101], v[154:157], v[170:173], v[98:101]
	v_mfma_f32_16x16x32_bf16 v[94:97], v[158:161], v[166:169], v[94:97]
	v_mfma_f32_16x16x32_bf16 v[94:97], v[162:165], v[170:173], v[94:97]
	v_mfma_f32_16x16x32_bf16 v[90:93], v[150:153], v[174:177], v[90:93]
	v_mfma_f32_16x16x32_bf16 v[90:93], v[154:157], v[202:205], v[90:93]
	v_mfma_f32_16x16x32_bf16 v[86:89], v[158:161], v[174:177], v[86:89]
	v_mfma_f32_16x16x32_bf16 v[86:89], v[162:165], v[202:205], v[86:89]
	v_mfma_f32_16x16x32_bf16 v[82:85], v[150:153], v[206:209], v[82:85]
	v_mfma_f32_16x16x32_bf16 v[82:85], v[154:157], v[210:213], v[82:85]
	v_mfma_f32_16x16x32_bf16 v[78:81], v[158:161], v[206:209], v[78:81]
	v_mfma_f32_16x16x32_bf16 v[78:81], v[162:165], v[210:213], v[78:81]
	v_mfma_f32_16x16x32_bf16 v[74:77], v[150:153], v[214:217], v[74:77]
	v_mfma_f32_16x16x32_bf16 v[74:77], v[154:157], v[218:221], v[74:77]
	v_mfma_f32_16x16x32_bf16 v[70:73], v[158:161], v[214:217], v[70:73]
	v_mfma_f32_16x16x32_bf16 v[70:73], v[162:165], v[218:221], v[70:73]
	s_barrier
	s_add_i32 s84, s78, s63
	s_mov_b32 m0, s84
	ds_read_b128 v[166:169], v230 offset:16384
	ds_read_b128 v[170:173], v230 offset:17408
	ds_read_b128 v[174:177], v230 offset:18432
	ds_read_b128 v[202:205], v230 offset:19456
	ds_read_b128 v[206:209], v230 offset:20480
	ds_read_b128 v[210:213], v230 offset:21504
	ds_read_b128 v[214:217], v230 offset:22528
	ds_read_b128 v[218:221], v230 offset:23552
	global_load_lds_dwordx4 v180, s[56:57]
	s_add_i32 m0, s84, 0x2000
	s_add_u32 s84, s56, 0x100000
	s_addc_u32 s85, s57, 0
	s_add_i32 s86, s79, s63
	global_load_lds_dwordx4 v184, s[56:57]
	s_mov_b32 m0, s86
	s_nop 0
	global_load_lds_dwordx4 v180, s[84:85]
	s_add_i32 m0, s86, 0x2000
	s_nop 0
	global_load_lds_dwordx4 v184, s[84:85]
	s_mov_b32 m0, s64
	s_nop 0
	global_load_lds_dwordx4 v178, s[58:59]
	s_mov_b32 m0, s65
	s_nop 0
	global_load_lds_dwordx4 v182, s[58:59]
	s_waitcnt vmcnt(8)
	s_cbranch_vccnz .Ldefl_1153_1
	s_waitcnt lgkmcnt(0)
.Ldefl_1153_1:
	s_barrier
	s_waitcnt lgkmcnt(0)
	v_mfma_f32_16x16x32_bf16 v[66:69], v[134:137], v[166:169], v[66:69]
	v_mfma_f32_16x16x32_bf16 v[66:69], v[138:141], v[170:173], v[66:69]
	v_mfma_f32_16x16x32_bf16 v[62:65], v[142:145], v[166:169], v[62:65]
	v_mfma_f32_16x16x32_bf16 v[62:65], v[146:149], v[170:173], v[62:65]
	v_mfma_f32_16x16x32_bf16 v[58:61], v[134:137], v[174:177], v[58:61]
	v_mfma_f32_16x16x32_bf16 v[58:61], v[138:141], v[202:205], v[58:61]
	v_mfma_f32_16x16x32_bf16 v[54:57], v[142:145], v[174:177], v[54:57]
	v_mfma_f32_16x16x32_bf16 v[54:57], v[146:149], v[202:205], v[54:57]
	v_mfma_f32_16x16x32_bf16 v[50:53], v[134:137], v[206:209], v[50:53]
	v_mfma_f32_16x16x32_bf16 v[50:53], v[138:141], v[210:213], v[50:53]
	v_mfma_f32_16x16x32_bf16 v[46:49], v[142:145], v[206:209], v[46:49]
	v_mfma_f32_16x16x32_bf16 v[46:49], v[146:149], v[210:213], v[46:49]
	v_mfma_f32_16x16x32_bf16 v[42:45], v[134:137], v[214:217], v[42:45]
	v_mfma_f32_16x16x32_bf16 v[42:45], v[138:141], v[218:221], v[42:45]
	v_mfma_f32_16x16x32_bf16 v[38:41], v[142:145], v[214:217], v[38:41]
	v_mfma_f32_16x16x32_bf16 v[38:41], v[146:149], v[218:221], v[38:41]
	v_mfma_f32_16x16x32_bf16 v[34:37], v[150:153], v[166:169], v[34:37]
	v_mfma_f32_16x16x32_bf16 v[34:37], v[154:157], v[170:173], v[34:37]
	v_mfma_f32_16x16x32_bf16 v[30:33], v[158:161], v[166:169], v[30:33]
	v_mfma_f32_16x16x32_bf16 v[30:33], v[162:165], v[170:173], v[30:33]
	v_mfma_f32_16x16x32_bf16 v[26:29], v[150:153], v[174:177], v[26:29]
	v_mfma_f32_16x16x32_bf16 v[26:29], v[154:157], v[202:205], v[26:29]
	v_mfma_f32_16x16x32_bf16 v[22:25], v[158:161], v[174:177], v[22:25]
	v_mfma_f32_16x16x32_bf16 v[22:25], v[162:165], v[202:205], v[22:25]
	v_mfma_f32_16x16x32_bf16 v[18:21], v[150:153], v[206:209], v[18:21]
	v_mfma_f32_16x16x32_bf16 v[18:21], v[154:157], v[210:213], v[18:21]
	v_mfma_f32_16x16x32_bf16 v[14:17], v[158:161], v[206:209], v[14:17]
	v_mfma_f32_16x16x32_bf16 v[14:17], v[162:165], v[210:213], v[14:17]
	v_mfma_f32_16x16x32_bf16 v[10:13], v[150:153], v[214:217], v[10:13]
	v_mfma_f32_16x16x32_bf16 v[10:13], v[154:157], v[218:221], v[10:13]
	v_mfma_f32_16x16x32_bf16 v[6:9], v[158:161], v[214:217], v[6:9]
	v_mfma_f32_16x16x32_bf16 v[6:9], v[162:165], v[218:221], v[6:9]
	s_barrier
	s_add_i32 s84, 0, 0x18000
	s_add_i32 s85, 0, 0x1c000
	ds_read_b128 v[134:137], v246
	ds_read_b128 v[138:141], v246 offset:1024
	ds_read_b128 v[142:145], v246 offset:2048
	ds_read_b128 v[146:149], v246 offset:3072
	ds_read_b128 v[150:153], v247
	ds_read_b128 v[154:157], v247 offset:1024
	ds_read_b128 v[158:161], v247 offset:2048
	ds_read_b128 v[162:165], v247 offset:3072
	s_add_u32 s100, s58, 0x80
	s_addc_u32 s101, s59, 0
	s_add_u32 s58, s58, 0x100000
	s_addc_u32 s59, s59, 0
	s_mov_b32 m0, s67
	ds_read_b128 v[166:169], v230 offset:32768
	ds_read_b128 v[170:173], v230 offset:33792
	ds_read_b128 v[174:177], v230 offset:34816
	ds_read_b128 v[202:205], v230 offset:35840
	ds_read_b128 v[206:209], v230 offset:36864
	ds_read_b128 v[210:213], v230 offset:37888
	ds_read_b128 v[214:217], v230 offset:38912
	ds_read_b128 v[218:221], v230 offset:39936
	global_load_lds_dwordx4 v178, s[58:59]
	s_mov_b32 m0, s68
	s_nop 0
	global_load_lds_dwordx4 v182, s[58:59]
	s_waitcnt vmcnt(8)
	s_cbranch_vccnz .Ldefl_1153_2
	s_waitcnt lgkmcnt(0)
.Ldefl_1153_2:
	s_barrier
	s_waitcnt lgkmcnt(0)
	v_mfma_f32_16x16x32_bf16 v[2:5], v[134:137], v[166:169], v[2:5]
	v_mfma_f32_16x16x32_bf16 v[2:5], v[138:141], v[170:173], v[2:5]
	v_mfma_f32_16x16x32_bf16 v[126:129], v[142:145], v[166:169], v[126:129]
	v_mfma_f32_16x16x32_bf16 v[126:129], v[146:149], v[170:173], v[126:129]
	v_mfma_f32_16x16x32_bf16 v[122:125], v[134:137], v[174:177], v[122:125]
	v_mfma_f32_16x16x32_bf16 v[122:125], v[138:141], v[202:205], v[122:125]
	v_mfma_f32_16x16x32_bf16 v[118:121], v[142:145], v[174:177], v[118:121]
	v_mfma_f32_16x16x32_bf16 v[118:121], v[146:149], v[202:205], v[118:121]
	v_mfma_f32_16x16x32_bf16 v[114:117], v[134:137], v[206:209], v[114:117]
	v_mfma_f32_16x16x32_bf16 v[114:117], v[138:141], v[210:213], v[114:117]
	v_mfma_f32_16x16x32_bf16 v[110:113], v[142:145], v[206:209], v[110:113]
	v_mfma_f32_16x16x32_bf16 v[110:113], v[146:149], v[210:213], v[110:113]
	v_mfma_f32_16x16x32_bf16 v[106:109], v[134:137], v[214:217], v[106:109]
	v_mfma_f32_16x16x32_bf16 v[106:109], v[138:141], v[218:221], v[106:109]
	v_mfma_f32_16x16x32_bf16 v[102:105], v[142:145], v[214:217], v[102:105]
	v_mfma_f32_16x16x32_bf16 v[102:105], v[146:149], v[218:221], v[102:105]
	v_mfma_f32_16x16x32_bf16 v[98:101], v[150:153], v[166:169], v[98:101]
	v_mfma_f32_16x16x32_bf16 v[98:101], v[154:157], v[170:173], v[98:101]
	v_mfma_f32_16x16x32_bf16 v[94:97], v[158:161], v[166:169], v[94:97]
	v_mfma_f32_16x16x32_bf16 v[94:97], v[162:165], v[170:173], v[94:97]
	v_mfma_f32_16x16x32_bf16 v[90:93], v[150:153], v[174:177], v[90:93]
	v_mfma_f32_16x16x32_bf16 v[90:93], v[154:157], v[202:205], v[90:93]
	v_mfma_f32_16x16x32_bf16 v[86:89], v[158:161], v[174:177], v[86:89]
	v_mfma_f32_16x16x32_bf16 v[86:89], v[162:165], v[202:205], v[86:89]
	v_mfma_f32_16x16x32_bf16 v[82:85], v[150:153], v[206:209], v[82:85]
	v_mfma_f32_16x16x32_bf16 v[82:85], v[154:157], v[210:213], v[82:85]
	v_mfma_f32_16x16x32_bf16 v[78:81], v[158:161], v[206:209], v[78:81]
	v_mfma_f32_16x16x32_bf16 v[78:81], v[162:165], v[210:213], v[78:81]
	v_mfma_f32_16x16x32_bf16 v[74:77], v[150:153], v[214:217], v[74:77]
	v_mfma_f32_16x16x32_bf16 v[74:77], v[154:157], v[218:221], v[74:77]
	v_mfma_f32_16x16x32_bf16 v[70:73], v[158:161], v[214:217], v[70:73]
	v_mfma_f32_16x16x32_bf16 v[70:73], v[162:165], v[218:221], v[70:73]
	s_barrier
	s_add_i32 s58, s84, s63
	s_add_u32 s98, s56, 0x80
	s_addc_u32 s99, s57, 0
	s_mov_b32 m0, s58
	ds_read_b128 v[166:169], v230 offset:49152
	ds_read_b128 v[170:173], v230 offset:50176
	ds_read_b128 v[174:177], v230 offset:51200
	ds_read_b128 v[202:205], v230 offset:52224
	ds_read_b128 v[206:209], v230 offset:53248
	ds_read_b128 v[210:213], v230 offset:54272
	ds_read_b128 v[214:217], v230 offset:55296
	ds_read_b128 v[218:221], v230 offset:56320
	global_load_lds_dwordx4 v180, s[98:99]
	s_add_i32 m0, s58, 0x2000
	s_add_u32 s56, s56, 0x100080
	s_addc_u32 s57, s57, 0
	s_add_i32 s58, s85, s63
	global_load_lds_dwordx4 v184, s[98:99]
	s_mov_b32 m0, s58
	s_nop 0
	global_load_lds_dwordx4 v180, s[56:57]
	s_add_i32 m0, s58, 0x2000
	s_nop 0
	global_load_lds_dwordx4 v184, s[56:57]
	s_mov_b32 m0, s74
	s_nop 0
	global_load_lds_dwordx4 v178, s[100:101]
	s_mov_b32 m0, s75
	s_nop 0
	global_load_lds_dwordx4 v182, s[100:101]
	s_waitcnt vmcnt(8)
	s_cbranch_vccnz .Ldefl_1153_3
	s_waitcnt lgkmcnt(0)
.Ldefl_1153_3:
	s_barrier
	s_waitcnt lgkmcnt(0)
	v_mfma_f32_16x16x32_bf16 v[66:69], v[134:137], v[166:169], v[66:69]
	v_mfma_f32_16x16x32_bf16 v[66:69], v[138:141], v[170:173], v[66:69]
	v_mfma_f32_16x16x32_bf16 v[62:65], v[142:145], v[166:169], v[62:65]
	v_mfma_f32_16x16x32_bf16 v[62:65], v[146:149], v[170:173], v[62:65]
	v_mfma_f32_16x16x32_bf16 v[58:61], v[134:137], v[174:177], v[58:61]
	v_mfma_f32_16x16x32_bf16 v[58:61], v[138:141], v[202:205], v[58:61]
	v_mfma_f32_16x16x32_bf16 v[54:57], v[142:145], v[174:177], v[54:57]
	v_mfma_f32_16x16x32_bf16 v[54:57], v[146:149], v[202:205], v[54:57]
	v_mfma_f32_16x16x32_bf16 v[50:53], v[134:137], v[206:209], v[50:53]
	v_mfma_f32_16x16x32_bf16 v[50:53], v[138:141], v[210:213], v[50:53]
	v_mfma_f32_16x16x32_bf16 v[46:49], v[142:145], v[206:209], v[46:49]
	v_mfma_f32_16x16x32_bf16 v[46:49], v[146:149], v[210:213], v[46:49]
	v_mfma_f32_16x16x32_bf16 v[42:45], v[134:137], v[214:217], v[42:45]
	v_mfma_f32_16x16x32_bf16 v[42:45], v[138:141], v[218:221], v[42:45]
	v_mfma_f32_16x16x32_bf16 v[38:41], v[142:145], v[214:217], v[38:41]
	v_mfma_f32_16x16x32_bf16 v[38:41], v[146:149], v[218:221], v[38:41]
	v_mfma_f32_16x16x32_bf16 v[34:37], v[150:153], v[166:169], v[34:37]
	v_mfma_f32_16x16x32_bf16 v[34:37], v[154:157], v[170:173], v[34:37]
	v_mfma_f32_16x16x32_bf16 v[30:33], v[158:161], v[166:169], v[30:33]
	v_mfma_f32_16x16x32_bf16 v[30:33], v[162:165], v[170:173], v[30:33]
	v_mfma_f32_16x16x32_bf16 v[26:29], v[150:153], v[174:177], v[26:29]
	v_mfma_f32_16x16x32_bf16 v[26:29], v[154:157], v[202:205], v[26:29]
	v_mfma_f32_16x16x32_bf16 v[22:25], v[158:161], v[174:177], v[22:25]
	v_mfma_f32_16x16x32_bf16 v[22:25], v[162:165], v[202:205], v[22:25]
	v_mfma_f32_16x16x32_bf16 v[18:21], v[150:153], v[206:209], v[18:21]
	v_mfma_f32_16x16x32_bf16 v[18:21], v[154:157], v[210:213], v[18:21]
	v_mfma_f32_16x16x32_bf16 v[14:17], v[158:161], v[206:209], v[14:17]
	v_mfma_f32_16x16x32_bf16 v[14:17], v[162:165], v[210:213], v[14:17]
	v_mfma_f32_16x16x32_bf16 v[10:13], v[150:153], v[214:217], v[10:13]
	v_mfma_f32_16x16x32_bf16 v[10:13], v[154:157], v[218:221], v[10:13]
	v_mfma_f32_16x16x32_bf16 v[6:9], v[158:161], v[214:217], v[6:9]
	v_mfma_f32_16x16x32_bf16 v[6:9], v[162:165], v[218:221], v[6:9]
	s_barrier
	s_add_i32 s83, s83, 2
	s_add_u32 s10, s10, 0x100
	s_addc_u32 s11, s11, 0
	s_cmp_gt_u32 s83, 61
	s_cbranch_scc0 .LBB0_1153
	s_and_b64 vcc, exec, s[36:37]
	s_cbranch_vccz .LBB0_1156
	s_barrier

.LBB0_1324:
	s_add_u32 s24, s24, 0x2b0080
	s_addc_u32 s25, s25, 0
	s_add_u32 s47, s26, 0x100
	v_mov_b32_e32 v2, 0
	s_addc_u32 s48, s27, 0
	s_mov_b32 s49, -2
	v_mov_b64_e32 v[2:3], 0
	v_mov_b64_e32 v[4:5], 0
	v_mov_b64_e32 v[6:7], 0
	v_mov_b64_e32 v[8:9], 0
	v_mov_b64_e32 v[10:11], 0
	v_mov_b64_e32 v[12:13], 0
	v_mov_b64_e32 v[14:15], 0
	v_mov_b64_e32 v[16:17], 0
	v_mov_b64_e32 v[18:19], 0
	v_mov_b64_e32 v[20:21], 0
	v_mov_b64_e32 v[22:23], 0
	v_mov_b64_e32 v[24:25], 0
	v_mov_b64_e32 v[26:27], 0
	v_mov_b64_e32 v[28:29], 0
	v_mov_b64_e32 v[30:31], 0
	v_mov_b64_e32 v[32:33], 0
	v_mov_b64_e32 v[34:35], 0
	v_mov_b64_e32 v[36:37], 0
	v_mov_b64_e32 v[38:39], 0
	v_mov_b64_e32 v[40:41], 0
	v_mov_b64_e32 v[42:43], 0
	v_mov_b64_e32 v[44:45], 0
	v_mov_b64_e32 v[46:47], 0
	v_mov_b64_e32 v[48:49], 0
	v_mov_b64_e32 v[50:51], 0
	v_mov_b64_e32 v[52:53], 0
	v_mov_b64_e32 v[54:55], 0
	v_mov_b64_e32 v[56:57], 0
	v_mov_b64_e32 v[58:59], 0
	v_mov_b64_e32 v[60:61], 0
	v_mov_b64_e32 v[62:63], 0
	v_mov_b64_e32 v[64:65], 0
	v_mov_b64_e32 v[66:67], 0
	v_mov_b64_e32 v[68:69], 0
	v_mov_b64_e32 v[70:71], 0
	v_mov_b64_e32 v[72:73], 0
	v_mov_b64_e32 v[82:83], 0
	v_mov_b64_e32 v[84:85], 0
	v_mov_b64_e32 v[86:87], 0
	v_mov_b64_e32 v[88:89], 0
	s_waitcnt vmcnt(0)
	v_mov_b64_e32 v[74:75], 0
	v_mov_b64_e32 v[76:77], 0
	v_mov_b64_e32 v[78:79], 0
	v_mov_b64_e32 v[80:81], 0
	v_mov_b64_e32 v[90:91], 0
	v_mov_b64_e32 v[92:93], 0
	v_mov_b64_e32 v[94:95], 0
	v_mov_b64_e32 v[96:97], 0
	v_mov_b64_e32 v[98:99], 0
	v_mov_b64_e32 v[100:101], 0
	v_mov_b64_e32 v[102:103], 0
	v_mov_b64_e32 v[104:105], 0
	v_mov_b64_e32 v[106:107], 0
	v_mov_b64_e32 v[108:109], 0
	v_mov_b64_e32 v[110:111], 0
	v_mov_b64_e32 v[112:113], 0
	v_mov_b64_e32 v[114:115], 0
	v_mov_b64_e32 v[116:117], 0
	v_mov_b64_e32 v[118:119], 0
	v_mov_b64_e32 v[120:121], 0
	v_mov_b64_e32 v[122:123], 0
	v_mov_b64_e32 v[124:125], 0
	v_mov_b64_e32 v[126:127], 0
	v_mov_b64_e32 v[128:129], 0
	v_add_u32_e32 v246, 0x18000, v174
	v_add_u32_e32 v247, 0x1c000, v174
	v_cmp_gt_u32_e32 vcc, 0x100, v0
.LBB0_1325:
	ds_read_b128 v[130:133], v176
	ds_read_b128 v[134:137], v176 offset:1024
	ds_read_b128 v[138:141], v176 offset:2048
	ds_read_b128 v[142:145], v176 offset:3072
	ds_read_b128 v[146:149], v177
	ds_read_b128 v[166:169], v177 offset:1024
	ds_read_b128 v[170:173], v177 offset:2048
	ds_read_b128 v[180:183], v177 offset:3072
	s_add_u32 s26, s24, 0xffd50080
	s_addc_u32 s27, s25, -1
	s_cmpk_eq_i32 s49, 0xa8
	s_cselect_b32 s29, s5, s27
	s_cselect_b32 s28, s4, s26
	s_cselect_b32 s27, s23, s48
	s_cselect_b32 s26, s22, s47
	s_add_i32 m0, s33, 0xc000
	ds_read_b128 v[184:187], v178
	ds_read_b128 v[188:191], v178 offset:1024
	ds_read_b128 v[192:195], v178 offset:2048
	ds_read_b128 v[196:199], v178 offset:3072
	ds_read_b128 v[200:203], v178 offset:4096
	ds_read_b128 v[204:207], v178 offset:5120
	ds_read_b128 v[208:211], v178 offset:6144
	ds_read_b128 v[212:215], v178 offset:7168
	global_load_lds_dwordx4 v158, s[24:25]
	s_add_i32 m0, s33, 0xe000
	s_nop 0
	global_load_lds_dwordx4 v160, s[24:25]
	s_waitcnt vmcnt(8)
	s_cbranch_vccnz .Ldefl_1325_0
	s_waitcnt lgkmcnt(0)
.Ldefl_1325_0:
	s_barrier
	s_waitcnt lgkmcnt(0)
	v_mfma_f32_16x16x32_bf16 v[126:129], v[130:133], v[184:187], v[126:129]
	v_mfma_f32_16x16x32_bf16 v[126:129], v[134:137], v[188:191], v[126:129]
	v_mfma_f32_16x16x32_bf16 v[122:125], v[138:141], v[184:187], v[122:125]
	v_mfma_f32_16x16x32_bf16 v[122:125], v[142:145], v[188:191], v[122:125]
	v_mfma_f32_16x16x32_bf16 v[110:113], v[130:133], v[192:195], v[110:113]
	v_mfma_f32_16x16x32_bf16 v[110:113], v[134:137], v[196:199], v[110:113]
	v_mfma_f32_16x16x32_bf16 v[106:109], v[138:141], v[192:195], v[106:109]
	v_mfma_f32_16x16x32_bf16 v[106:109], v[142:145], v[196:199], v[106:109]
	v_mfma_f32_16x16x32_bf16 v[94:97], v[130:133], v[200:203], v[94:97]
	v_mfma_f32_16x16x32_bf16 v[94:97], v[134:137], v[204:207], v[94:97]
	v_mfma_f32_16x16x32_bf16 v[90:93], v[138:141], v[200:203], v[90:93]
	v_mfma_f32_16x16x32_bf16 v[90:93], v[142:145], v[204:207], v[90:93]
	v_mfma_f32_16x16x32_bf16 v[78:81], v[130:133], v[208:211], v[78:81]
	v_mfma_f32_16x16x32_bf16 v[78:81], v[134:137], v[212:215], v[78:81]
	v_mfma_f32_16x16x32_bf16 v[74:77], v[138:141], v[208:211], v[74:77]
	v_mfma_f32_16x16x32_bf16 v[74:77], v[142:145], v[212:215], v[74:77]
	v_mfma_f32_16x16x32_bf16 v[118:121], v[146:149], v[184:187], v[118:121]
	v_mfma_f32_16x16x32_bf16 v[118:121], v[166:169], v[188:191], v[118:121]
	v_mfma_f32_16x16x32_bf16 v[114:117], v[170:173], v[184:187], v[114:117]
	v_mfma_f32_16x16x32_bf16 v[114:117], v[180:183], v[188:191], v[114:117]
	v_mfma_f32_16x16x32_bf16 v[102:105], v[146:149], v[192:195], v[102:105]
	v_mfma_f32_16x16x32_bf16 v[102:105], v[166:169], v[196:199], v[102:105]
	v_mfma_f32_16x16x32_bf16 v[98:101], v[170:173], v[192:195], v[98:101]
	v_mfma_f32_16x16x32_bf16 v[98:101], v[180:183], v[196:199], v[98:101]
	v_mfma_f32_16x16x32_bf16 v[86:89], v[146:149], v[200:203], v[86:89]
	v_mfma_f32_16x16x32_bf16 v[86:89], v[166:169], v[204:207], v[86:89]
	v_mfma_f32_16x16x32_bf16 v[82:85], v[170:173], v[200:203], v[82:85]
	v_mfma_f32_16x16x32_bf16 v[82:85], v[180:183], v[204:207], v[82:85]
	v_mfma_f32_16x16x32_bf16 v[70:73], v[146:149], v[208:211], v[70:73]
	v_mfma_f32_16x16x32_bf16 v[70:73], v[166:169], v[212:215], v[70:73]
	v_mfma_f32_16x16x32_bf16 v[66:69], v[170:173], v[208:211], v[66:69]
	v_mfma_f32_16x16x32_bf16 v[66:69], v[180:183], v[212:215], v[66:69]
	s_barrier
	s_add_i32 s50, s41, s31
	s_mov_b32 m0, s50
	ds_read_b128 v[184:187], v178 offset:16384
	ds_read_b128 v[188:191], v178 offset:17408
	ds_read_b128 v[192:195], v178 offset:18432
	ds_read_b128 v[196:199], v178 offset:19456
	ds_read_b128 v[200:203], v178 offset:20480
	ds_read_b128 v[204:207], v178 offset:21504
	ds_read_b128 v[208:211], v178 offset:22528
	ds_read_b128 v[212:215], v178 offset:23552
	global_load_lds_dwordx4 v152, s[26:27]
	s_add_i32 m0, s50, 0x2000
	s_add_u32 s50, s26, 0x2b0000
	s_addc_u32 s51, s27, 0
	s_add_i32 s52, s42, s31
	global_load_lds_dwordx4 v156, s[26:27]
	s_mov_b32 m0, s52
	global_load_lds_dwordx4 v152, s[50:51]
	s_add_i32 m0, s52, 0x2000
	s_nop 0
	global_load_lds_dwordx4 v156, s[50:51]
	s_mov_b32 m0, s33
	s_nop 0
	global_load_lds_dwordx4 v150, s[28:29]
	s_mov_b32 m0, s34
	s_nop 0
	global_load_lds_dwordx4 v154, s[28:29]
	s_waitcnt vmcnt(8)
	s_cbranch_vccnz .Ldefl_1325_1
	s_waitcnt lgkmcnt(0)
.Ldefl_1325_1:
	s_barrier
	s_waitcnt lgkmcnt(0)
	v_mfma_f32_16x16x32_bf16 v[62:65], v[130:133], v[184:187], v[62:65]
	v_mfma_f32_16x16x32_bf16 v[62:65], v[134:137], v[188:191], v[62:65]
	v_mfma_f32_16x16x32_bf16 v[58:61], v[138:141], v[184:187], v[58:61]
	v_mfma_f32_16x16x32_bf16 v[58:61], v[142:145], v[188:191], v[58:61]
	v_mfma_f32_16x16x32_bf16 v[46:49], v[130:133], v[192:195], v[46:49]
	v_mfma_f32_16x16x32_bf16 v[46:49], v[134:137], v[196:199], v[46:49]
	v_mfma_f32_16x16x32_bf16 v[42:45], v[138:141], v[192:195], v[42:45]
	v_mfma_f32_16x16x32_bf16 v[42:45], v[142:145], v[196:199], v[42:45]
	v_mfma_f32_16x16x32_bf16 v[30:33], v[130:133], v[200:203], v[30:33]
	v_mfma_f32_16x16x32_bf16 v[30:33], v[134:137], v[204:207], v[30:33]
	v_mfma_f32_16x16x32_bf16 v[26:29], v[138:141], v[200:203], v[26:29]
	v_mfma_f32_16x16x32_bf16 v[26:29], v[142:145], v[204:207], v[26:29]
	v_mfma_f32_16x16x32_bf16 v[14:17], v[130:133], v[208:211], v[14:17]
	v_mfma_f32_16x16x32_bf16 v[14:17], v[134:137], v[212:215], v[14:17]
	v_mfma_f32_16x16x32_bf16 v[10:13], v[138:141], v[208:211], v[10:13]
	v_mfma_f32_16x16x32_bf16 v[10:13], v[142:145], v[212:215], v[10:13]
	v_mfma_f32_16x16x32_bf16 v[54:57], v[146:149], v[184:187], v[54:57]
	v_mfma_f32_16x16x32_bf16 v[54:57], v[166:169], v[188:191], v[54:57]
	v_mfma_f32_16x16x32_bf16 v[50:53], v[170:173], v[184:187], v[50:53]
	v_mfma_f32_16x16x32_bf16 v[50:53], v[180:183], v[188:191], v[50:53]
	v_mfma_f32_16x16x32_bf16 v[38:41], v[146:149], v[192:195], v[38:41]
	v_mfma_f32_16x16x32_bf16 v[38:41], v[166:169], v[196:199], v[38:41]
	v_mfma_f32_16x16x32_bf16 v[34:37], v[170:173], v[192:195], v[34:37]
	v_mfma_f32_16x16x32_bf16 v[34:37], v[180:183], v[196:199], v[34:37]
	v_mfma_f32_16x16x32_bf16 v[22:25], v[146:149], v[200:203], v[22:25]
	v_mfma_f32_16x16x32_bf16 v[22:25], v[166:169], v[204:207], v[22:25]
	v_mfma_f32_16x16x32_bf16 v[18:21], v[170:173], v[200:203], v[18:21]
	v_mfma_f32_16x16x32_bf16 v[18:21], v[180:183], v[204:207], v[18:21]
	v_mfma_f32_16x16x32_bf16 v[6:9], v[146:149], v[208:211], v[6:9]
	v_mfma_f32_16x16x32_bf16 v[6:9], v[166:169], v[212:215], v[6:9]
	v_mfma_f32_16x16x32_bf16 v[2:5], v[170:173], v[208:211], v[2:5]
	v_mfma_f32_16x16x32_bf16 v[2:5], v[180:183], v[212:215], v[2:5]
	s_barrier
	s_add_i32 s50, 0, 0x18000
	s_add_i32 s51, 0, 0x1c000
	ds_read_b128 v[130:133], v246
	ds_read_b128 v[134:137], v246 offset:1024
	ds_read_b128 v[138:141], v246 offset:2048
	ds_read_b128 v[142:145], v246 offset:3072
	ds_read_b128 v[146:149], v247
	ds_read_b128 v[166:169], v247 offset:1024
	ds_read_b128 v[170:173], v247 offset:2048
	ds_read_b128 v[180:183], v247 offset:3072
	s_add_u32 s98, s28, 0x80
	s_addc_u32 s99, s29, 0
	s_add_u32 s28, s28, 0x2b0000
	s_addc_u32 s29, s29, 0
	s_mov_b32 m0, s35
	ds_read_b128 v[184:187], v178 offset:32768
	ds_read_b128 v[188:191], v178 offset:33792
	ds_read_b128 v[192:195], v178 offset:34816
	ds_read_b128 v[196:199], v178 offset:35840
	ds_read_b128 v[200:203], v178 offset:36864
	ds_read_b128 v[204:207], v178 offset:37888
	ds_read_b128 v[208:211], v178 offset:38912
	ds_read_b128 v[212:215], v178 offset:39936
	global_load_lds_dwordx4 v150, s[28:29]
	s_mov_b32 m0, s36
	s_nop 0
	global_load_lds_dwordx4 v154, s[28:29]
	s_waitcnt vmcnt(8)
	s_cbranch_vccnz .Ldefl_1325_2
	s_waitcnt lgkmcnt(0)
.Ldefl_1325_2:
	s_barrier
	s_waitcnt lgkmcnt(0)
	v_mfma_f32_16x16x32_bf16 v[126:129], v[130:133], v[184:187], v[126:129]
	v_mfma_f32_16x16x32_bf16 v[126:129], v[134:137], v[188:191], v[126:129]
	v_mfma_f32_16x16x32_bf16 v[122:125], v[138:141], v[184:187], v[122:125]
	v_mfma_f32_16x16x32_bf16 v[122:125], v[142:145], v[188:191], v[122:125]
	v_mfma_f32_16x16x32_bf16 v[110:113], v[130:133], v[192:195], v[110:113]
	v_mfma_f32_16x16x32_bf16 v[110:113], v[134:137], v[196:199], v[110:113]
	v_mfma_f32_16x16x32_bf16 v[106:109], v[138:141], v[192:195], v[106:109]
	v_mfma_f32_16x16x32_bf16 v[106:109], v[142:145], v[196:199], v[106:109]
	v_mfma_f32_16x16x32_bf16 v[94:97], v[130:133], v[200:203], v[94:97]
	v_mfma_f32_16x16x32_bf16 v[94:97], v[134:137], v[204:207], v[94:97]
	v_mfma_f32_16x16x32_bf16 v[90:93], v[138:141], v[200:203], v[90:93]
	v_mfma_f32_16x16x32_bf16 v[90:93], v[142:145], v[204:207], v[90:93]
	v_mfma_f32_16x16x32_bf16 v[78:81], v[130:133], v[208:211], v[78:81]
	v_mfma_f32_16x16x32_bf16 v[78:81], v[134:137], v[212:215], v[78:81]
	v_mfma_f32_16x16x32_bf16 v[74:77], v[138:141], v[208:211], v[74:77]
	v_mfma_f32_16x16x32_bf16 v[74:77], v[142:145], v[212:215], v[74:77]
	v_mfma_f32_16x16x32_bf16 v[118:121], v[146:149], v[184:187], v[118:121]
	v_mfma_f32_16x16x32_bf16 v[118:121], v[166:169], v[188:191], v[118:121]
	v_mfma_f32_16x16x32_bf16 v[114:117], v[170:173], v[184:187], v[114:117]
	v_mfma_f32_16x16x32_bf16 v[114:117], v[180:183], v[188:191], v[114:117]
	v_mfma_f32_16x16x32_bf16 v[102:105], v[146:149], v[192:195], v[102:105]
	v_mfma_f32_16x16x32_bf16 v[102:105], v[166:169], v[196:199], v[102:105]
	v_mfma_f32_16x16x32_bf16 v[98:101], v[170:173], v[192:195], v[98:101]
	v_mfma_f32_16x16x32_bf16 v[98:101], v[180:183], v[196:199], v[98:101]
	v_mfma_f32_16x16x32_bf16 v[86:89], v[146:149], v[200:203], v[86:89]
	v_mfma_f32_16x16x32_bf16 v[86:89], v[166:169], v[204:207], v[86:89]
	v_mfma_f32_16x16x32_bf16 v[82:85], v[170:173], v[200:203], v[82:85]
	v_mfma_f32_16x16x32_bf16 v[82:85], v[180:183], v[204:207], v[82:85]
	v_mfma_f32_16x16x32_bf16 v[70:73], v[146:149], v[208:211], v[70:73]
	v_mfma_f32_16x16x32_bf16 v[70:73], v[166:169], v[212:215], v[70:73]
	v_mfma_f32_16x16x32_bf16 v[66:69], v[170:173], v[208:211], v[66:69]
	v_mfma_f32_16x16x32_bf16 v[66:69], v[180:183], v[212:215], v[66:69]
	s_barrier
	s_add_i32 s28, s50, s31
	s_mov_b32 m0, s28
	ds_read_b128 v[184:187], v178 offset:49152
	ds_read_b128 v[188:191], v178 offset:50176
	ds_read_b128 v[192:195], v178 offset:51200
	ds_read_b128 v[196:199], v178 offset:52224
	ds_read_b128 v[200:203], v178 offset:53248
	ds_read_b128 v[204:207], v178 offset:54272
	ds_read_b128 v[208:211], v178 offset:55296
	ds_read_b128 v[212:215], v178 offset:56320
	s_add_u32 s26, s26, 0x80
	s_addc_u32 s27, s27, 0
	global_load_lds_dwordx4 v152, s[26:27]
	s_add_i32 m0, s28, 0x2000
	s_add_i32 s28, s51, s31
	global_load_lds_dwordx4 v156, s[26:27]
	s_add_u32 s26, s26, 0x2b0000
	s_addc_u32 s27, s27, 0
	s_mov_b32 m0, s28
	s_nop 0
	global_load_lds_dwordx4 v152, s[26:27]
	s_add_i32 m0, s28, 0x2000
	s_nop 0
	global_load_lds_dwordx4 v156, s[26:27]
	s_mov_b32 m0, s38
	s_nop 0
	global_load_lds_dwordx4 v150, s[98:99]
	s_mov_b32 m0, s39
	s_nop 0
	global_load_lds_dwordx4 v154, s[98:99]
	s_waitcnt vmcnt(8)
	s_cbranch_vccnz .Ldefl_1325_3
	s_waitcnt lgkmcnt(0)
.Ldefl_1325_3:
	s_barrier
	s_waitcnt lgkmcnt(0)
	v_mfma_f32_16x16x32_bf16 v[62:65], v[130:133], v[184:187], v[62:65]
	v_mfma_f32_16x16x32_bf16 v[62:65], v[134:137], v[188:191], v[62:65]
	v_mfma_f32_16x16x32_bf16 v[58:61], v[138:141], v[184:187], v[58:61]
	v_mfma_f32_16x16x32_bf16 v[58:61], v[142:145], v[188:191], v[58:61]
	v_mfma_f32_16x16x32_bf16 v[46:49], v[130:133], v[192:195], v[46:49]
	v_mfma_f32_16x16x32_bf16 v[46:49], v[134:137], v[196:199], v[46:49]
	v_mfma_f32_16x16x32_bf16 v[42:45], v[138:141], v[192:195], v[42:45]
	v_mfma_f32_16x16x32_bf16 v[42:45], v[142:145], v[196:199], v[42:45]
	v_mfma_f32_16x16x32_bf16 v[30:33], v[130:133], v[200:203], v[30:33]
	v_mfma_f32_16x16x32_bf16 v[30:33], v[134:137], v[204:207], v[30:33]
	v_mfma_f32_16x16x32_bf16 v[26:29], v[138:141], v[200:203], v[26:29]
	v_mfma_f32_16x16x32_bf16 v[26:29], v[142:145], v[204:207], v[26:29]
	v_mfma_f32_16x16x32_bf16 v[14:17], v[130:133], v[208:211], v[14:17]
	v_mfma_f32_16x16x32_bf16 v[14:17], v[134:137], v[212:215], v[14:17]
	v_mfma_f32_16x16x32_bf16 v[10:13], v[138:141], v[208:211], v[10:13]
	v_mfma_f32_16x16x32_bf16 v[10:13], v[142:145], v[212:215], v[10:13]
	v_mfma_f32_16x16x32_bf16 v[54:57], v[146:149], v[184:187], v[54:57]
	v_mfma_f32_16x16x32_bf16 v[54:57], v[166:169], v[188:191], v[54:57]
	v_mfma_f32_16x16x32_bf16 v[50:53], v[170:173], v[184:187], v[50:53]
	v_mfma_f32_16x16x32_bf16 v[50:53], v[180:183], v[188:191], v[50:53]
	v_mfma_f32_16x16x32_bf16 v[38:41], v[146:149], v[192:195], v[38:41]
	v_mfma_f32_16x16x32_bf16 v[38:41], v[166:169], v[196:199], v[38:41]
	v_mfma_f32_16x16x32_bf16 v[34:37], v[170:173], v[192:195], v[34:37]
	v_mfma_f32_16x16x32_bf16 v[34:37], v[180:183], v[196:199], v[34:37]
	v_mfma_f32_16x16x32_bf16 v[22:25], v[146:149], v[200:203], v[22:25]
	v_mfma_f32_16x16x32_bf16 v[22:25], v[166:169], v[204:207], v[22:25]
	v_mfma_f32_16x16x32_bf16 v[18:21], v[170:173], v[200:203], v[18:21]
	v_mfma_f32_16x16x32_bf16 v[18:21], v[180:183], v[204:207], v[18:21]
	v_mfma_f32_16x16x32_bf16 v[6:9], v[146:149], v[208:211], v[6:9]
	v_mfma_f32_16x16x32_bf16 v[6:9], v[166:169], v[212:215], v[6:9]
	v_mfma_f32_16x16x32_bf16 v[2:5], v[170:173], v[208:211], v[2:5]
	v_mfma_f32_16x16x32_bf16 v[2:5], v[180:183], v[212:215], v[2:5]
	s_barrier
	s_add_i32 s49, s49, 2
	s_add_u32 s24, s24, 0x100
	s_addc_u32 s25, s25, 0
	s_add_u32 s47, s47, 0x100
	s_addc_u32 s48, s48, 0
	s_cmpk_gt_u32 s49, 0xa9
	s_cbranch_scc0 .LBB0_1325
	s_and_b64 vcc, exec, s[10:11]
	s_cbranch_vccz .LBB0_1328
	s_barrier
